# P7 main ConvGLU epilogue: depthwise conv rewritten as v_fma + 4 v_fmac_f32_dpp per output (no dpp-mov/cndmask temps), list-rescheduled
# speedup vs baseline: 1.0116x; 1.0011x over previous
; __device__ __forceinline__ float fma_s(float a, float b, float c) { float d; asm("v_fma_f32 %0, %1, %2, %3" : "=v"(d) : "v"(a), "v"(b), "v"(c)); return d; }
; #define PG8_ROR1(x) dpp_ror1(x)
; #define PG8_ROR15(x) dpp_ror15(x)
;     __device__ __forceinline__ void run(f32x4 (&acc)[2][2][4][2], const Unit& un, int wr, int wc, int fr, int fq, PG8_LAS unsigned char* xl) const {
;     ...
;             for (int m = 0; m < 4; ++m) { const float iv = __builtin_amdgcn_rsqf(ssq[(size_t)un.pm * BM + wr * 64 + fr + ai * HALF + m * 16] * inv_n + eps);
; #pragma unroll
;                 for (int bj = 0; bj < 2; ++bj)
; #pragma unroll
;                     for (int n = 0; n < 2; ++n) acc[ai][bj][m][n] = acc[ai][bj][m][n] * iv; }
;     ...
;                     for (int e = 0; e < 4; ++e) {
;                         const float g = acc[ai][0][m][n][e], v = acc[ai][1][m][n][e];
;                         const float gpe = m > 0 ? PG8_ROR1(acc[ai][0][m - 1][n][e]) : hpg[e], vpe = m > 0 ? PG8_ROR1(acc[ai][1][m - 1][n][e]) : hpv[e];
;                         const float gne = m < 3 ? PG8_ROR15(acc[ai][0][m + 1][n][e]) : hng[e], vne = m < 3 ? PG8_ROR15(acc[ai][1][m + 1][n][e]) : hnv[e];
;                         const float gpi = PG8_ROR1(g), vpi = PG8_ROR1(v), gni = PG8_ROR15(g), vni = PG8_ROR15(v);
;                         const float gp = e0 ? gpe : gpi, vp = e0 ? vpe : vpi, gn = e15 ? gne : gni, vn = e15 ? vne : vni;
;                         const float cg = fma_s(w2g[e], gn, fma_s(w1g[e], g, fma_s(w0g[e], gp, bg[e]))), cv = fma_s(w2v[e], vn, fma_s(w1v[e], v, fma_s(w0v[e], vp, bv[e])));
;                         o[e] = (cg * cv) * __builtin_amdgcn_rcpf(1.0f + __builtin_amdgcn_exp2f(cg * -1.4426950408889634f));
.LBB0_798:
	v_fmamk_f32 v214, v214, 0x39800000, v244
	v_fmamk_f32 v216, v216, 0x39800000, v244
	v_rsq_f32_e32 v214, v214
	v_rsq_f32_e32 v216, v216
	v_cmp_eq_u32_e64 s[10:11], 0, v210
	v_cmp_eq_u32_e64 s[12:13], 15, v210
	v_pk_mul_f32 v[220:221], v[104:105], v[214:215] op_sel_hi:[1,0]
	v_pk_mul_f32 v[104:105], v[106:107], v[216:217] op_sel_hi:[1,0]
	s_waitcnt lgkmcnt(0)
	v_pk_mul_f32 v[110:111], v[110:111], v[214:215] op_sel_hi:[1,0]
	s_waitcnt lgkmcnt(0)
	v_pk_mul_f32 v[218:219], v[102:103], v[214:215] op_sel_hi:[1,0]
	v_pk_mul_f32 v[102:103], v[108:109], v[216:217] op_sel_hi:[1,0]
	v_fma_f32 v248, v138, v126, v154
	v_fma_f32 v224, v142, v130, v158
	v_fma_f32 v249, v139, v127, v155
	v_fmac_f32_dpp v248, v126, v114 row_shr:1 row_mask:0xf bank_mask:0xf
	v_fmac_f32_dpp v224, v130, v150 row_shr:1 row_mask:0xf bank_mask:0xf
	v_fmac_f32_dpp v249, v127, v115 row_shr:1 row_mask:0xf bank_mask:0xf
	v_fmac_f32_dpp v248, v174, v114 row_shl:15 row_mask:0xf bank_mask:0xf
	v_fmac_f32_dpp v224, v170, v150 row_shl:15 row_mask:0xf bank_mask:0xf
	v_fmac_f32_dpp v249, v175, v115 row_shl:15 row_mask:0xf bank_mask:0xf
	v_fmac_f32_dpp v248, v126, v134 row_shl:1 row_mask:0xf bank_mask:0xf
	v_fmac_f32_dpp v224, v130, v146 row_shl:1 row_mask:0xf bank_mask:0xf
	v_fmac_f32_dpp v249, v127, v135 row_shl:1 row_mask:0xf bank_mask:0xf
	v_fmac_f32_dpp v248, v110, v134 row_shr:15 row_mask:0xf bank_mask:0xf
	v_mov_b32_e32 v174, v248
	v_fmac_f32_dpp v224, v218, v146 row_shr:15 row_mask:0xf bank_mask:0xf
	v_fmac_f32_dpp v249, v111, v135 row_shr:15 row_mask:0xf bank_mask:0xf
	v_mov_b32_e32 v175, v249
	v_fma_f32 v225, v143, v131, v159
	v_pk_mul_f32 v[112:113], v[112:113], v[214:215] op_sel_hi:[1,0]
	v_fma_f32 v170, v140, v128, v156
	v_fmac_f32_dpp v225, v131, v151 row_shr:1 row_mask:0xf bank_mask:0xf
	v_fma_f32 v250, v144, v132, v160
	v_fmac_f32_dpp v170, v128, v116 row_shr:1 row_mask:0xf bank_mask:0xf
	v_fmac_f32_dpp v225, v171, v151 row_shl:15 row_mask:0xf bank_mask:0xf
	v_fmac_f32_dpp v250, v132, v152 row_shr:1 row_mask:0xf bank_mask:0xf
	v_fmac_f32_dpp v170, v176, v116 row_shl:15 row_mask:0xf bank_mask:0xf
	v_fmac_f32_dpp v225, v131, v147 row_shl:1 row_mask:0xf bank_mask:0xf
	v_fmac_f32_dpp v250, v172, v152 row_shl:15 row_mask:0xf bank_mask:0xf
	v_fmac_f32_dpp v170, v128, v136 row_shl:1 row_mask:0xf bank_mask:0xf
	v_fmac_f32_dpp v225, v219, v147 row_shr:15 row_mask:0xf bank_mask:0xf
	v_fmac_f32_dpp v250, v132, v148 row_shl:1 row_mask:0xf bank_mask:0xf
	v_fmac_f32_dpp v170, v112, v136 row_shr:15 row_mask:0xf bank_mask:0xf
	v_fma_f32 v171, v141, v129, v157
	v_fmac_f32_dpp v250, v220, v148 row_shr:15 row_mask:0xf bank_mask:0xf
	v_mov_b32_e32 v176, v250
	v_fmac_f32_dpp v171, v129, v117 row_shr:1 row_mask:0xf bank_mask:0xf
	v_fma_f32 v251, v145, v133, v161
	v_pk_mul_f32 v[98:99], v[98:99], v[216:217] op_sel_hi:[1,0]
	v_fmac_f32_dpp v171, v177, v117 row_shl:15 row_mask:0xf bank_mask:0xf
	v_fmac_f32_dpp v251, v133, v153 row_shr:1 row_mask:0xf bank_mask:0xf
	v_fma_f32 v228, v138, v110, v154
	v_fmac_f32_dpp v171, v129, v137 row_shl:1 row_mask:0xf bank_mask:0xf
	v_fmac_f32_dpp v251, v173, v153 row_shl:15 row_mask:0xf bank_mask:0xf
	v_fmac_f32_dpp v228, v110, v114 row_shr:1 row_mask:0xf bank_mask:0xf
	v_fmac_f32_dpp v171, v113, v137 row_shr:15 row_mask:0xf bank_mask:0xf
	v_fmac_f32_dpp v251, v133, v149 row_shl:1 row_mask:0xf bank_mask:0xf
	v_fmac_f32_dpp v228, v126, v114 row_shl:15 row_mask:0xf bank_mask:0xf
	v_fma_f32 v234, v142, v218, v158
	v_fmac_f32_dpp v251, v221, v149 row_shr:15 row_mask:0xf bank_mask:0xf
	v_mov_b32_e32 v177, v251
	v_fmac_f32_dpp v228, v110, v134 row_shl:1 row_mask:0xf bank_mask:0xf
	v_fmac_f32_dpp v234, v218, v150 row_shr:1 row_mask:0xf bank_mask:0xf
	v_fma_f32 v229, v139, v111, v155
	v_fmac_f32_dpp v228, v104, v134 row_shr:15 row_mask:0xf bank_mask:0xf
	v_fmac_f32_dpp v234, v130, v150 row_shl:15 row_mask:0xf bank_mask:0xf
	v_fmac_f32_dpp v229, v111, v115 row_shr:1 row_mask:0xf bank_mask:0xf
	v_fma_f32 v235, v143, v219, v159
	v_fmac_f32_dpp v234, v218, v146 row_shl:1 row_mask:0xf bank_mask:0xf
	v_fmac_f32_dpp v229, v127, v115 row_shl:15 row_mask:0xf bank_mask:0xf
	v_fmac_f32_dpp v235, v219, v151 row_shr:1 row_mask:0xf bank_mask:0xf
	v_fmac_f32_dpp v234, v98, v146 row_shr:15 row_mask:0xf bank_mask:0xf
	v_fmac_f32_dpp v229, v111, v135 row_shl:1 row_mask:0xf bank_mask:0xf
	v_fmac_f32_dpp v235, v131, v151 row_shl:15 row_mask:0xf bank_mask:0xf
	v_pk_mul_f32 v[100:101], v[100:101], v[216:217] op_sel_hi:[1,0]
	v_fmac_f32_dpp v229, v105, v135 row_shr:15 row_mask:0xf bank_mask:0xf
	v_fmac_f32_dpp v235, v219, v147 row_shl:1 row_mask:0xf bank_mask:0xf
	v_fma_f32 v252, v140, v112, v156
	v_fma_f32 v236, v142, v98, v158
	v_fmac_f32_dpp v235, v99, v147 row_shr:15 row_mask:0xf bank_mask:0xf
	v_fmac_f32_dpp v252, v112, v116 row_shr:1 row_mask:0xf bank_mask:0xf
	v_fma_f32 v226, v144, v220, v160
	v_fma_f32 v253, v141, v113, v157
	v_fma_f32 v237, v143, v99, v159
	v_fmac_f32_dpp v252, v128, v116 row_shl:15 row_mask:0xf bank_mask:0xf
	v_fmac_f32_dpp v226, v220, v152 row_shr:1 row_mask:0xf bank_mask:0xf
	v_fmac_f32_dpp v253, v113, v117 row_shr:1 row_mask:0xf bank_mask:0xf
	v_fmac_f32_dpp v252, v112, v136 row_shl:1 row_mask:0xf bank_mask:0xf
	v_fmac_f32_dpp v226, v132, v152 row_shl:15 row_mask:0xf bank_mask:0xf
	v_fmac_f32_dpp v253, v129, v117 row_shl:15 row_mask:0xf bank_mask:0xf
	v_fmac_f32_dpp v252, v102, v136 row_shr:15 row_mask:0xf bank_mask:0xf
	v_fmac_f32_dpp v226, v220, v148 row_shl:1 row_mask:0xf bank_mask:0xf
	v_fmac_f32_dpp v253, v113, v137 row_shl:1 row_mask:0xf bank_mask:0xf
	v_fma_f32 v227, v145, v221, v161
	v_fmac_f32_dpp v226, v100, v148 row_shr:15 row_mask:0xf bank_mask:0xf
; #define PG8_LAS __attribute__((address_space(3)))
; #define PG8_GAS __attribute__((address_space(1)))
; __device__ __forceinline__ float fma_s(float a, float b, float c) { float d; asm("v_fma_f32 %0, %1, %2, %3" : "=v"(d) : "v"(a), "v"(b), "v"(c)); return d; }
; #define PG8_ROR1(x) dpp_ror1(x)
;     __device__ __forceinline__ void run(f32x4 (&acc)[2][2][4][2], const Unit& un, int wr, int wc, int fr, int fq, PG8_LAS unsigned char* xl) const {
;     ...
;             for (int n = 0; n < 2; ++n) {
;                 const int j = un.pn * 128 + cl + 4 * n;
;                 const f32x4 w0g = *(const PG8_GAS f32x4*)(cw + j), w1g = *(const PG8_GAS f32x4*)(cw + nup + j), w2g = *(const PG8_GAS f32x4*)(cw + 2 * (size_t)nup + j), bg = *(const PG8_GAS f32x4*)(cb + j);
;                 const f32x4 w0v = *(const PG8_GAS f32x4*)(cw + dff + j), w1v = *(const PG8_GAS f32x4*)(cw + nup + dff + j), w2v = *(const PG8_GAS f32x4*)(cw + 2 * (size_t)nup + dff + j), bv = *(const PG8_GAS f32x4*)(cb + dff + j);
;                 f32x4 hpg, hpv, hng, hnv;
;                 if (blk > 0) { hpg = *(const PG8_LAS f32x4*)(X + ((blk - 1) * 2 + 1) * 256 + cl + 4 * n); hpv = *(const PG8_LAS f32x4*)(X + ((blk - 1) * 2 + 1) * 256 + 128 + cl + 4 * n); } else { hpg = (f32x4){0.f, 0.f, 0.f, 0.f}; hpv = hpg; }
;                 if (blk < 3) { hng = *(const PG8_LAS f32x4*)(X + ((blk + 1) * 2 + 0) * 256 + cl + 4 * n); hnv = *(const PG8_LAS f32x4*)(X + ((blk + 1) * 2 + 0) * 256 + 128 + cl + 4 * n); } else { hng = (f32x4){0.f, 0.f, 0.f, 0.f}; hnv = hng; }
;     ...
;                     for (int e = 0; e < 4; ++e) {
;                         const float g = acc[ai][0][m][n][e], v = acc[ai][1][m][n][e];
;                         const float gpe = m > 0 ? PG8_ROR1(acc[ai][0][m - 1][n][e]) : hpg[e], vpe = m > 0 ? PG8_ROR1(acc[ai][1][m - 1][n][e]) : hpv[e];
;                         const float gne = m < 3 ? PG8_ROR15(acc[ai][0][m + 1][n][e]) : hng[e], vne = m < 3 ? PG8_ROR15(acc[ai][1][m + 1][n][e]) : hnv[e];
;                         const float gpi = PG8_ROR1(g), vpi = PG8_ROR1(v), gni = PG8_ROR15(g), vni = PG8_ROR15(v);
;                         const float gp = e0 ? gpe : gpi, vp = e0 ? vpe : vpi, gn = e15 ? gne : gni, vn = e15 ? vne : vni;
;                         const float cg = fma_s(w2g[e], gn, fma_s(w1g[e], g, fma_s(w0g[e], gp, bg[e]))), cv = fma_s(w2v[e], vn, fma_s(w1v[e], v, fma_s(w0v[e], vp, bv[e])));
	v_fmac_f32_dpp v253, v103, v137 row_shr:15 row_mask:0xf bank_mask:0xf
	v_fmac_f32_dpp v227, v221, v153 row_shr:1 row_mask:0xf bank_mask:0xf
	v_fma_f32 v232, v138, v104, v154
	v_fmac_f32_dpp v236, v98, v150 row_shr:1 row_mask:0xf bank_mask:0xf
	v_fmac_f32_dpp v227, v133, v153 row_shl:15 row_mask:0xf bank_mask:0xf
	v_fmac_f32_dpp v232, v104, v114 row_shr:1 row_mask:0xf bank_mask:0xf
	v_fmac_f32_dpp v236, v218, v150 row_shl:15 row_mask:0xf bank_mask:0xf
	v_mov_b32_e32 v218, v252
	v_fmac_f32_dpp v227, v221, v149 row_shl:1 row_mask:0xf bank_mask:0xf
	v_fmac_f32_dpp v232, v110, v114 row_shl:15 row_mask:0xf bank_mask:0xf
	v_fmac_f32_dpp v236, v98, v146 row_shl:1 row_mask:0xf bank_mask:0xf
	v_fmac_f32_dpp v227, v101, v149 row_shr:15 row_mask:0xf bank_mask:0xf
	v_fmac_f32_dpp v232, v104, v134 row_shl:1 row_mask:0xf bank_mask:0xf
	v_fmac_f32_dpp v236, v122, v146 row_shr:15 row_mask:0xf bank_mask:0xf
	v_fma_f32 v233, v139, v105, v155
	v_fmac_f32_dpp v232, v118, v134 row_shr:15 row_mask:0xf bank_mask:0xf
	v_fmac_f32_dpp v237, v99, v151 row_shr:1 row_mask:0xf bank_mask:0xf
	v_fmac_f32_dpp v233, v105, v115 row_shr:1 row_mask:0xf bank_mask:0xf
	v_fma_f32 v172, v140, v102, v156
	v_fmac_f32_dpp v237, v219, v151 row_shl:15 row_mask:0xf bank_mask:0xf
	v_mov_b32_e32 v219, v253
	v_fmac_f32_dpp v233, v111, v115 row_shl:15 row_mask:0xf bank_mask:0xf
	v_fmac_f32_dpp v237, v99, v147 row_shl:1 row_mask:0xf bank_mask:0xf
	v_fmac_f32_dpp v172, v102, v116 row_shr:1 row_mask:0xf bank_mask:0xf
	v_fmac_f32_dpp v233, v105, v135 row_shl:1 row_mask:0xf bank_mask:0xf
	v_fmac_f32_dpp v237, v123, v147 row_shr:15 row_mask:0xf bank_mask:0xf
	v_fmac_f32_dpp v172, v112, v116 row_shl:15 row_mask:0xf bank_mask:0xf
	v_fmac_f32_dpp v233, v119, v135 row_shr:15 row_mask:0xf bank_mask:0xf
	v_fma_f32 v255, v144, v100, v160
	v_fmac_f32_dpp v172, v102, v136 row_shl:1 row_mask:0xf bank_mask:0xf
	v_fma_f32 v173, v141, v103, v157
	v_fmac_f32_dpp v255, v100, v152 row_shr:1 row_mask:0xf bank_mask:0xf
	v_fmac_f32_dpp v172, v120, v136 row_shr:15 row_mask:0xf bank_mask:0xf
	v_fmac_f32_dpp v173, v103, v117 row_shr:1 row_mask:0xf bank_mask:0xf
	v_fmac_f32_dpp v255, v220, v152 row_shl:15 row_mask:0xf bank_mask:0xf
	v_fma_f32 v179, v145, v101, v161
	v_fmac_f32_dpp v173, v113, v117 row_shl:15 row_mask:0xf bank_mask:0xf
	v_fmac_f32_dpp v255, v100, v148 row_shl:1 row_mask:0xf bank_mask:0xf
	v_fmac_f32_dpp v179, v101, v153 row_shr:1 row_mask:0xf bank_mask:0xf
	v_fmac_f32_dpp v173, v103, v137 row_shl:1 row_mask:0xf bank_mask:0xf
	v_fmac_f32_dpp v255, v124, v148 row_shr:15 row_mask:0xf bank_mask:0xf
	v_mov_b32_e32 v220, v255
	v_fmac_f32_dpp v173, v121, v137 row_shr:15 row_mask:0xf bank_mask:0xf
	v_fmac_f32_dpp v179, v221, v153 row_shl:15 row_mask:0xf bank_mask:0xf
	v_fma_f32 v222, v138, v118, v154
	v_fma_f32 v230, v142, v122, v158
	v_fmac_f32_dpp v179, v101, v149 row_shl:1 row_mask:0xf bank_mask:0xf
	v_fmac_f32_dpp v222, v118, v114 row_shr:1 row_mask:0xf bank_mask:0xf
	v_fmac_f32_dpp v230, v122, v150 row_shr:1 row_mask:0xf bank_mask:0xf
	v_fmac_f32_dpp v179, v125, v149 row_shr:15 row_mask:0xf bank_mask:0xf
	v_mov_b32_e32 v221, v179
	v_fmac_f32_dpp v222, v104, v114 row_shl:15 row_mask:0xf bank_mask:0xf
	v_fmac_f32_dpp v230, v98, v150 row_shl:15 row_mask:0xf bank_mask:0xf
	v_fma_f32 v223, v139, v119, v155
	v_fmac_f32_dpp v222, v118, v134 row_shl:1 row_mask:0xf bank_mask:0xf
	v_fmac_f32_dpp v230, v122, v146 row_shl:1 row_mask:0xf bank_mask:0xf
	v_fmac_f32_dpp v223, v119, v115 row_shr:1 row_mask:0xf bank_mask:0xf
	v_fmac_f32_dpp v222, v166, v134 row_shr:15 row_mask:0xf bank_mask:0xf
	v_fmac_f32_dpp v230, v162, v146 row_shr:15 row_mask:0xf bank_mask:0xf
	v_fmac_f32_dpp v223, v105, v115 row_shl:15 row_mask:0xf bank_mask:0xf
	v_fma_f32 v231, v143, v123, v159
	v_fma_f32 v138, v140, v120, v156
	v_fmac_f32_dpp v223, v119, v135 row_shl:1 row_mask:0xf bank_mask:0xf
	v_fmac_f32_dpp v231, v123, v151 row_shr:1 row_mask:0xf bank_mask:0xf
	v_fmac_f32_dpp v138, v120, v116 row_shr:1 row_mask:0xf bank_mask:0xf
	v_fmac_f32_dpp v223, v167, v135 row_shr:15 row_mask:0xf bank_mask:0xf
	v_fmac_f32_dpp v231, v99, v151 row_shl:15 row_mask:0xf bank_mask:0xf
	v_fmac_f32_dpp v138, v102, v116 row_shl:15 row_mask:0xf bank_mask:0xf
	v_fma_f32 v154, v144, v124, v160
	v_fmac_f32_dpp v231, v123, v147 row_shl:1 row_mask:0xf bank_mask:0xf
	v_fmac_f32_dpp v138, v120, v136 row_shl:1 row_mask:0xf bank_mask:0xf
	v_fmac_f32_dpp v154, v124, v152 row_shr:1 row_mask:0xf bank_mask:0xf
	v_fmac_f32_dpp v231, v163, v147 row_shr:15 row_mask:0xf bank_mask:0xf
	v_fmac_f32_dpp v138, v168, v136 row_shr:15 row_mask:0xf bank_mask:0xf
	v_fmac_f32_dpp v154, v100, v152 row_shl:15 row_mask:0xf bank_mask:0xf
	v_fma_f32 v139, v141, v121, v157
	v_fma_f32 v155, v145, v125, v161
	v_fmac_f32_dpp v154, v124, v148 row_shl:1 row_mask:0xf bank_mask:0xf
	v_fmac_f32_dpp v139, v121, v117 row_shr:1 row_mask:0xf bank_mask:0xf
	v_fmac_f32_dpp v155, v125, v153 row_shr:1 row_mask:0xf bank_mask:0xf
	v_fmac_f32_dpp v154, v164, v148 row_shr:15 row_mask:0xf bank_mask:0xf
	v_fmac_f32_dpp v139, v103, v117 row_shl:15 row_mask:0xf bank_mask:0xf
	v_fmac_f32_dpp v155, v101, v153 row_shl:15 row_mask:0xf bank_mask:0xf
	v_or_b32_e32 v102, 4, v212
	v_fmac_f32_dpp v139, v121, v137 row_shl:1 row_mask:0xf bank_mask:0xf
	v_fmac_f32_dpp v155, v125, v149 row_shl:1 row_mask:0xf bank_mask:0xf
	v_ashrrev_i32_e32 v103, 31, v102
	v_fmac_f32_dpp v139, v169, v137 row_shr:15 row_mask:0xf bank_mask:0xf
	v_fmac_f32_dpp v155, v165, v149 row_shr:15 row_mask:0xf bank_mask:0xf
	v_lshlrev_b64 v[126:127], 2, v[102:103]
	v_lshl_add_u64 v[156:157], s[48:49], 0, v[126:127]
	ds_read_b128 v[98:101], v247 offset:16
	v_lshl_add_u64 v[158:159], s[50:51], 0, v[126:127]
	ds_read_b128 v[106:109], v247 offset:528
	ds_read_b128 v[102:105], v247 offset:1040
	ds_read_b128 v[118:121], v247 offset:3088
	v_lshl_add_u64 v[160:161], s[52:53], 0, v[126:127]
	v_lshl_add_u64 v[164:165], s[56:57], 0, v[126:127]
	v_lshl_add_u64 v[166:167], s[58:59], 0, v[126:127]
	v_lshl_add_u64 v[162:163], s[54:55], 0, v[126:127]
	ds_read_b128 v[110:113], v247 offset:1552
	ds_read_b128 v[114:117], v247 offset:2064
	ds_read_b128 v[122:125], v247 offset:2576
	ds_read_b128 v[126:129], v247 offset:3600
	v_mov_b32_e32 v130, 0
	s_and_b64 vcc, exec, s[14:15]
	v_mov_b32_e32 v144, 0
	v_mov_b32_e32 v145, 0
	v_mov_b32_e32 v146, 0
	v_mov_b32_e32 v147, 0
	v_mov_b32_e32 v148, 0
	v_mov_b32_e32 v149, 0
	v_mov_b32_e32 v150, 0
	v_mov_b32_e32 v151, 0
	s_cbranch_vccnz .LBB0_800
	ds_read_b128 v[148:151], v217 offset:16
	ds_read_b128 v[144:147], v215 offset:16

; #define PG8_GAS __attribute__((address_space(1)))
; __device__ __forceinline__ unsigned cvt_pk_bf16(float lo, float hi) { const f32x2c v = {lo, hi}; return __builtin_bit_cast(unsigned, __builtin_convertvector(v, bf16x2c)); }
;     __device__ __forceinline__ void run(f32x4 (&acc)[2][2][4][2], const Unit& un, int wr, int wc, int fr, int fq, PG8_LAS unsigned char* xl) const {
;     ...
;             for (int m = 0; m < 4; ++m) { const float iv = __builtin_amdgcn_rsqf(ssq[(size_t)un.pm * BM + wr * 64 + fr + ai * HALF + m * 16] * inv_n + eps);
; #pragma unroll
;                 for (int bj = 0; bj < 2; ++bj)
; #pragma unroll
;                     for (int n = 0; n < 2; ++n) acc[ai][bj][m][n] = acc[ai][bj][m][n] * iv; }
;     ...
;                         o[e] = (cg * cv) * __builtin_amdgcn_rcpf(1.0f + __builtin_amdgcn_exp2f(cg * -1.4426950408889634f));
;                     }
;                     if (n == 0) { keep[m].x = cvt_pk_bf16(o[0], o[1]); keep[m].y = cvt_pk_bf16(o[2], o[3]); }
;                     else { u32x4 w; w.x = keep[m].x; w.y = keep[m].y; w.z = cvt_pk_bf16(o[0], o[1]); w.w = cvt_pk_bf16(o[2], o[3]);
;                         *(PG8_GAS u32x4*)(act + (size_t)(row0 + ai * HALF + m * 16) * dff + j - 4) = w; }
.LBB0_802:
	v_mul_f32_e32 v140, 0xbfb8aa3b, v174
	v_mul_f32_e32 v141, 0xbfb8aa3b, v175
	v_exp_f32_e32 v140, v140
	v_exp_f32_e32 v141, v141
	v_pk_mul_f32 v[142:143], v[174:175], v[224:225]
	v_pk_mul_f32 v[152:153], v[170:171], v[176:177]
	v_add_f32_e32 v140, 1.0, v140
	v_add_f32_e32 v141, 1.0, v141
	v_rcp_f32_e32 v140, v140
	v_rcp_f32_e32 v141, v141
	v_pk_mul_f32 v[168:169], v[218:219], v[226:227]
	v_mov_b32_e32 v215, v214
	v_mov_b32_e32 v217, v216
	v_pk_mul_f32 v[140:141], v[142:143], v[140:141]
	v_mul_f32_e32 v142, 0xbfb8aa3b, v170
	v_mul_f32_e32 v143, 0xbfb8aa3b, v171
	v_exp_f32_e32 v142, v142
	v_exp_f32_e32 v143, v143
	v_pk_mul_f32 v[170:171], v[172:173], v[220:221]
	s_lshl_b32 s14, s76, 8
	v_add_f32_e32 v142, 1.0, v142
	v_add_f32_e32 v143, 1.0, v143
	v_rcp_f32_e32 v142, v142
	v_rcp_f32_e32 v143, v143
	s_add_i32 s14, s14, s34
	v_pk_mul_f32 v[142:143], v[152:153], v[142:143]
	v_cvt_pk_bf16_f32 v152, v140, v141
	v_mul_f32_e32 v140, 0xbfb8aa3b, v228
	v_mul_f32_e32 v141, 0xbfb8aa3b, v229
	v_exp_f32_e32 v140, v140
	v_exp_f32_e32 v141, v141
	v_cvt_pk_bf16_f32 v153, v142, v143
	v_pk_mul_f32 v[142:143], v[228:229], v[234:235]
	v_add_f32_e32 v140, 1.0, v140
	v_add_f32_e32 v141, 1.0, v141
	v_rcp_f32_e32 v140, v140
	v_rcp_f32_e32 v141, v141
	s_nop 0
	v_pk_mul_f32 v[140:141], v[142:143], v[140:141]
	v_mul_f32_e32 v142, 0xbfb8aa3b, v218
	v_mul_f32_e32 v143, 0xbfb8aa3b, v219
	v_exp_f32_e32 v142, v142
	v_exp_f32_e32 v143, v143
	v_add_f32_e32 v142, 1.0, v142
	v_add_f32_e32 v143, 1.0, v143
	v_rcp_f32_e32 v142, v142
	v_rcp_f32_e32 v143, v143
	s_nop 0
	v_pk_mul_f32 v[168:169], v[168:169], v[142:143]
	v_cvt_pk_bf16_f32 v142, v140, v141
	v_mul_f32_e32 v140, 0xbfb8aa3b, v232
	v_mul_f32_e32 v141, 0xbfb8aa3b, v233
	v_exp_f32_e32 v140, v140
	v_exp_f32_e32 v141, v141
	v_cvt_pk_bf16_f32 v143, v168, v169
	v_pk_mul_f32 v[168:169], v[232:233], v[236:237]
	v_add_f32_e32 v140, 1.0, v140
	v_add_f32_e32 v141, 1.0, v141
	v_rcp_f32_e32 v140, v140
	v_rcp_f32_e32 v141, v141
	s_nop 0
	v_pk_mul_f32 v[140:141], v[168:169], v[140:141]
	v_mul_f32_e32 v168, 0xbfb8aa3b, v172
	v_mul_f32_e32 v169, 0xbfb8aa3b, v173
	v_exp_f32_e32 v168, v168
	v_exp_f32_e32 v169, v169
	v_cvt_pk_bf16_f32 v140, v140, v141
	v_add_u32_e32 v172, s14, v210
	v_add_f32_e32 v168, 1.0, v168
	v_add_f32_e32 v169, 1.0, v169
	v_rcp_f32_e32 v168, v168
	v_rcp_f32_e32 v169, v169
	s_nop 0
	v_pk_mul_f32 v[168:169], v[170:171], v[168:169]
	v_cvt_pk_bf16_f32 v141, v168, v169
	v_mul_f32_e32 v168, 0xbfb8aa3b, v222
	v_mul_f32_e32 v169, 0xbfb8aa3b, v223
	v_exp_f32_e32 v168, v168
	v_exp_f32_e32 v169, v169
	v_pk_mul_f32 v[170:171], v[222:223], v[230:231]
	v_add_f32_e32 v168, 1.0, v168
	v_add_f32_e32 v169, 1.0, v169
	v_rcp_f32_e32 v168, v168
	v_rcp_f32_e32 v169, v169
	s_waitcnt lgkmcnt(1)
	v_pk_mul_f32 v[168:169], v[170:171], v[168:169]
	v_mul_f32_e32 v170, 0xbfb8aa3b, v138
	v_mul_f32_e32 v171, 0xbfb8aa3b, v139
	v_exp_f32_e32 v170, v170
	v_exp_f32_e32 v171, v171
	v_pk_mul_f32 v[138:139], v[138:139], v[154:155]
	v_add_f32_e32 v170, 1.0, v170
	v_add_f32_e32 v171, 1.0, v171
	v_rcp_f32_e32 v170, v170
	v_rcp_f32_e32 v171, v171
	s_waitcnt lgkmcnt(0)
	v_pk_mul_f32 v[154:155], v[138:139], v[170:171]
	v_cvt_pk_bf16_f32 v139, v154, v155
	v_mov_b32_e32 v154, v214
	v_mov_b32_e32 v155, v214
	v_cvt_pk_bf16_f32 v138, v168, v169
	v_pk_mul_f32 v[168:169], v[86:87], v[214:215]
	v_pk_mul_f32 v[86:87], v[80:81], v[154:155]
	v_pk_mul_f32 v[80:81], v[82:83], v[216:217]
	v_pk_mul_f32 v[82:83], v[74:75], v[216:217]
	v_pk_mul_f32 v[88:89], v[88:89], v[154:155]
	v_mov_b32_e32 v154, v216
	v_mov_b32_e32 v155, v216
	v_pk_mul_f32 v[170:171], v[78:79], v[214:215]
	v_pk_mul_f32 v[78:79], v[84:85], v[154:155]
	s_waitcnt lgkmcnt(0)
	s_waitcnt lgkmcnt(0)
	v_fma_f32 v74, v106, v90, v118
	v_fma_f32 v84, v114, v94, v126
	v_pk_mul_f32 v[76:77], v[76:77], v[154:155]
	v_fmac_f32_dpp v74, v90, v98 row_shr:1 row_mask:0xf bank_mask:0xf
	v_fmac_f32_dpp v84, v94, v110 row_shr:1 row_mask:0xf bank_mask:0xf
	v_fma_f32 v181, v107, v91, v119
	v_fmac_f32_dpp v74, v148, v98 row_shl:15 row_mask:0xf bank_mask:0xf
	v_fmac_f32_dpp v84, v144, v110 row_shl:15 row_mask:0xf bank_mask:0xf
	v_fmac_f32_dpp v181, v91, v99 row_shr:1 row_mask:0xf bank_mask:0xf
	v_fmac_f32_dpp v74, v90, v102 row_shl:1 row_mask:0xf bank_mask:0xf
	v_fmac_f32_dpp v84, v94, v122 row_shl:1 row_mask:0xf bank_mask:0xf
	v_fmac_f32_dpp v181, v149, v99 row_shl:15 row_mask:0xf bank_mask:0xf
	v_fmac_f32_dpp v74, v168, v102 row_shr:15 row_mask:0xf bank_mask:0xf
	v_fmac_f32_dpp v84, v170, v122 row_shr:15 row_mask:0xf bank_mask:0xf
	v_mul_f32_e32 v75, 0xbfb8aa3b, v74
	v_exp_f32_e32 v75, v75
	v_fmac_f32_dpp v181, v91, v103 row_shl:1 row_mask:0xf bank_mask:0xf
	v_add_f32_e32 v75, 1.0, v75
	v_rcp_f32_e32 v144, v75
	v_fmac_f32_dpp v181, v169, v103 row_shr:15 row_mask:0xf bank_mask:0xf
	v_mov_b32_e32 v75, v181
	v_fma_f32 v85, v115, v95, v127
	v_fma_f32 v183, v108, v92, v120
	v_fma_f32 v185, v116, v96, v128
	v_fmac_f32_dpp v85, v95, v111 row_shr:1 row_mask:0xf bank_mask:0xf
	v_fmac_f32_dpp v183, v92, v100 row_shr:1 row_mask:0xf bank_mask:0xf
	v_fmac_f32_dpp v185, v96, v112 row_shr:1 row_mask:0xf bank_mask:0xf
	v_fmac_f32_dpp v85, v145, v111 row_shl:15 row_mask:0xf bank_mask:0xf
	v_mul_f32_e32 v145, 0xbfb8aa3b, v75
	v_exp_f32_e32 v145, v145
	v_fmac_f32_dpp v85, v95, v123 row_shl:1 row_mask:0xf bank_mask:0xf
	v_add_f32_e32 v145, 1.0, v145
	v_rcp_f32_e32 v145, v145
	v_fmac_f32_dpp v85, v171, v123 row_shr:15 row_mask:0xf bank_mask:0xf
	v_pk_mul_f32 v[74:75], v[74:75], v[84:85]
	v_pk_mul_f32 v[74:75], v[74:75], v[144:145]
	v_fmac_f32_dpp v183, v150, v100 row_shl:15 row_mask:0xf bank_mask:0xf
	v_fmac_f32_dpp v185, v146, v112 row_shl:15 row_mask:0xf bank_mask:0xf
; #define PG8_GAS __attribute__((address_space(1)))
; __device__ __forceinline__ unsigned cvt_pk_bf16(float lo, float hi) { const f32x2c v = {lo, hi}; return __builtin_bit_cast(unsigned, __builtin_convertvector(v, bf16x2c)); }
; __device__ __forceinline__ float fma_s(float a, float b, float c) { float d; asm("v_fma_f32 %0, %1, %2, %3" : "=v"(d) : "v"(a), "v"(b), "v"(c)); return d; }
; #define PG8_ROR1(x) dpp_ror1(x)
; #define PG8_ROR15(x) dpp_ror15(x)
;     __device__ __forceinline__ void run(f32x4 (&acc)[2][2][4][2], const Unit& un, int wr, int wc, int fr, int fq, PG8_LAS unsigned char* xl) const {
;     ...
;                 for (int m = 0; m < 4; ++m) {
;                     float o[4];
; #pragma unroll
;                     for (int e = 0; e < 4; ++e) {
;                         const float g = acc[ai][0][m][n][e], v = acc[ai][1][m][n][e];
;                         const float gpe = m > 0 ? PG8_ROR1(acc[ai][0][m - 1][n][e]) : hpg[e], vpe = m > 0 ? PG8_ROR1(acc[ai][1][m - 1][n][e]) : hpv[e];
;                         const float gne = m < 3 ? PG8_ROR15(acc[ai][0][m + 1][n][e]) : hng[e], vne = m < 3 ? PG8_ROR15(acc[ai][1][m + 1][n][e]) : hnv[e];
;                         const float gpi = PG8_ROR1(g), vpi = PG8_ROR1(v), gni = PG8_ROR15(g), vni = PG8_ROR15(v);
;                         const float gp = e0 ? gpe : gpi, vp = e0 ? vpe : vpi, gn = e15 ? gne : gni, vn = e15 ? vne : vni;
;                         const float cg = fma_s(w2g[e], gn, fma_s(w1g[e], g, fma_s(w0g[e], gp, bg[e]))), cv = fma_s(w2v[e], vn, fma_s(w1v[e], v, fma_s(w0v[e], vp, bv[e])));
;                         o[e] = (cg * cv) * __builtin_amdgcn_rcpf(1.0f + __builtin_amdgcn_exp2f(cg * -1.4426950408889634f));
;                     }
;                     if (n == 0) { keep[m].x = cvt_pk_bf16(o[0], o[1]); keep[m].y = cvt_pk_bf16(o[2], o[3]); }
;                     else { u32x4 w; w.x = keep[m].x; w.y = keep[m].y; w.z = cvt_pk_bf16(o[0], o[1]); w.w = cvt_pk_bf16(o[2], o[3]);
;                         *(PG8_GAS u32x4*)(act + (size_t)(row0 + ai * HALF + m * 16) * dff + j - 4) = w; }
	v_fma_f32 v248, v109, v93, v121
	v_fmac_f32_dpp v183, v92, v104 row_shl:1 row_mask:0xf bank_mask:0xf
	v_fmac_f32_dpp v185, v96, v124 row_shl:1 row_mask:0xf bank_mask:0xf
	v_fmac_f32_dpp v248, v93, v101 row_shr:1 row_mask:0xf bank_mask:0xf
	v_fmac_f32_dpp v183, v88, v104 row_shr:15 row_mask:0xf bank_mask:0xf
	v_mov_b32_e32 v84, v183
	v_fmac_f32_dpp v185, v86, v124 row_shr:15 row_mask:0xf bank_mask:0xf
	v_mov_b32_e32 v144, v185
	v_mul_f32_e32 v85, 0xbfb8aa3b, v84
	v_exp_f32_e32 v85, v85
	v_fmac_f32_dpp v248, v151, v101 row_shl:15 row_mask:0xf bank_mask:0xf
	v_add_f32_e32 v85, 1.0, v85
	v_rcp_f32_e32 v146, v85
	v_fmac_f32_dpp v248, v93, v105 row_shl:1 row_mask:0xf bank_mask:0xf
	v_fma_f32 v145, v117, v97, v129
	v_cvt_pk_bf16_f32 v154, v74, v75
	v_fmac_f32_dpp v248, v89, v105 row_shr:15 row_mask:0xf bank_mask:0xf
	v_mov_b32_e32 v85, v248
	v_fmac_f32_dpp v145, v97, v113 row_shr:1 row_mask:0xf bank_mask:0xf
	v_mov_b64_e32 v[74:75], s[24:25]
	v_fma_f32 v249, v106, v168, v118
	v_fmac_f32_dpp v145, v147, v113 row_shl:15 row_mask:0xf bank_mask:0xf
	v_mul_f32_e32 v147, 0xbfb8aa3b, v85
	v_exp_f32_e32 v147, v147
	v_fmac_f32_dpp v145, v97, v125 row_shl:1 row_mask:0xf bank_mask:0xf
	v_add_f32_e32 v147, 1.0, v147
	v_rcp_f32_e32 v147, v147
	v_fmac_f32_dpp v145, v87, v125 row_shr:15 row_mask:0xf bank_mask:0xf
	v_pk_mul_f32 v[84:85], v[84:85], v[144:145]
	v_pk_mul_f32 v[84:85], v[84:85], v[146:147]
	v_cvt_pk_bf16_f32 v155, v84, v85
	v_mad_i64_i32 v[84:85], s[14:15], v172, s5, v[74:75]
	v_lshlrev_b64 v[146:147], 1, v[212:213]
	v_lshl_add_u64 v[84:85], v[84:85], 0, v[146:147]
	global_store_dwordx4 v[84:85], v[152:155], off
	v_fmac_f32_dpp v249, v168, v98 row_shr:1 row_mask:0xf bank_mask:0xf
	v_fma_f32 v250, v114, v170, v126
	v_fma_f32 v251, v107, v169, v119
	v_fmac_f32_dpp v249, v90, v98 row_shl:15 row_mask:0xf bank_mask:0xf
	v_fmac_f32_dpp v250, v170, v110 row_shr:1 row_mask:0xf bank_mask:0xf
	v_fmac_f32_dpp v251, v169, v99 row_shr:1 row_mask:0xf bank_mask:0xf
	v_fmac_f32_dpp v249, v168, v102 row_shl:1 row_mask:0xf bank_mask:0xf
	v_fmac_f32_dpp v250, v94, v110 row_shl:15 row_mask:0xf bank_mask:0xf
	v_fmac_f32_dpp v251, v91, v99 row_shl:15 row_mask:0xf bank_mask:0xf
	v_fmac_f32_dpp v249, v80, v102 row_shr:15 row_mask:0xf bank_mask:0xf
	v_mov_b32_e32 v84, v249
	v_fmac_f32_dpp v250, v170, v122 row_shl:1 row_mask:0xf bank_mask:0xf
	v_mul_f32_e32 v85, 0xbfb8aa3b, v84
	v_exp_f32_e32 v85, v85
	v_fmac_f32_dpp v250, v82, v122 row_shr:15 row_mask:0xf bank_mask:0xf
	v_mov_b32_e32 v90, v250
	v_add_f32_e32 v85, 1.0, v85
	v_rcp_f32_e32 v94, v85
	v_fmac_f32_dpp v251, v169, v103 row_shl:1 row_mask:0xf bank_mask:0xf
	v_fma_f32 v91, v115, v171, v127
	v_fma_f32 v252, v108, v88, v120
	v_fma_f32 v253, v108, v78, v120
	v_fma_f32 v255, v108, v68, v120
	v_fmac_f32_dpp v251, v81, v103 row_shr:15 row_mask:0xf bank_mask:0xf
	v_mov_b32_e32 v85, v251
	v_fmac_f32_dpp v91, v171, v111 row_shr:1 row_mask:0xf bank_mask:0xf
	v_fmac_f32_dpp v252, v88, v100 row_shr:1 row_mask:0xf bank_mask:0xf
	v_fma_f32 v179, v116, v86, v128
	v_fma_f32 v181, v116, v76, v128
	v_fma_f32 v183, v116, v72, v128
	v_fmac_f32_dpp v91, v95, v111 row_shl:15 row_mask:0xf bank_mask:0xf
	v_mul_f32_e32 v95, 0xbfb8aa3b, v85
	v_exp_f32_e32 v95, v95
	v_fmac_f32_dpp v91, v171, v123 row_shl:1 row_mask:0xf bank_mask:0xf
	v_add_f32_e32 v95, 1.0, v95
	v_rcp_f32_e32 v95, v95
	v_fmac_f32_dpp v91, v83, v123 row_shr:15 row_mask:0xf bank_mask:0xf
	v_pk_mul_f32 v[84:85], v[84:85], v[90:91]
	v_pk_mul_f32 v[84:85], v[84:85], v[94:95]
	v_fmac_f32_dpp v252, v92, v100 row_shl:15 row_mask:0xf bank_mask:0xf
	v_fmac_f32_dpp v179, v86, v112 row_shr:1 row_mask:0xf bank_mask:0xf
	v_fma_f32 v185, v109, v89, v121
	v_fma_f32 v248, v109, v79, v121
	v_fma_f32 v249, v109, v69, v121
	v_fmac_f32_dpp v252, v88, v104 row_shl:1 row_mask:0xf bank_mask:0xf
	v_fmac_f32_dpp v179, v96, v112 row_shl:15 row_mask:0xf bank_mask:0xf
	v_fmac_f32_dpp v185, v89, v101 row_shr:1 row_mask:0xf bank_mask:0xf
	v_fmac_f32_dpp v252, v78, v104 row_shr:15 row_mask:0xf bank_mask:0xf
	v_fmac_f32_dpp v179, v86, v124 row_shl:1 row_mask:0xf bank_mask:0xf
	v_fmac_f32_dpp v185, v93, v101 row_shl:15 row_mask:0xf bank_mask:0xf
	v_cvt_pk_bf16_f32 v144, v84, v85
	v_fmac_f32_dpp v179, v76, v124 row_shr:15 row_mask:0xf bank_mask:0xf
	v_fmac_f32_dpp v185, v89, v105 row_shl:1 row_mask:0xf bank_mask:0xf
	v_add_u32_e32 v84, 16, v172
	v_mad_i64_i32 v[84:85], s[14:15], v84, s5, v[74:75]
	v_fmac_f32_dpp v185, v79, v105 row_shr:15 row_mask:0xf bank_mask:0xf
	v_lshl_add_u64 v[84:85], v[84:85], 0, v[146:147]
	v_fmac_f32_dpp v253, v78, v100 row_shr:1 row_mask:0xf bank_mask:0xf
	v_fmac_f32_dpp v181, v76, v112 row_shr:1 row_mask:0xf bank_mask:0xf
	v_fmac_f32_dpp v248, v79, v101 row_shr:1 row_mask:0xf bank_mask:0xf
	v_fmac_f32_dpp v253, v88, v100 row_shl:15 row_mask:0xf bank_mask:0xf
	v_mov_b32_e32 v88, v252
	v_mul_f32_e32 v90, 0xbfb8aa3b, v88
	v_exp_f32_e32 v90, v90
	v_fmac_f32_dpp v253, v78, v104 row_shl:1 row_mask:0xf bank_mask:0xf
	v_add_f32_e32 v90, 1.0, v90
	v_rcp_f32_e32 v90, v90
	v_fmac_f32_dpp v253, v68, v104 row_shr:15 row_mask:0xf bank_mask:0xf
	v_fmac_f32_dpp v181, v86, v112 row_shl:15 row_mask:0xf bank_mask:0xf
	v_mov_b32_e32 v86, v179
	v_fma_f32 v250, v117, v87, v129
	v_fma_f32 v251, v117, v77, v129
	v_fma_f32 v252, v117, v73, v129
	v_fmac_f32_dpp v250, v87, v113 row_shr:1 row_mask:0xf bank_mask:0xf
	v_fmac_f32_dpp v181, v76, v124 row_shl:1 row_mask:0xf bank_mask:0xf
	v_fmac_f32_dpp v248, v89, v101 row_shl:15 row_mask:0xf bank_mask:0xf
	v_mov_b32_e32 v89, v185
	v_mul_f32_e32 v91, 0xbfb8aa3b, v89
	v_exp_f32_e32 v91, v91
	v_fmac_f32_dpp v250, v97, v113 row_shl:15 row_mask:0xf bank_mask:0xf
; #define PG8_GAS __attribute__((address_space(1)))
; __device__ __forceinline__ unsigned cvt_pk_bf16(float lo, float hi) { const f32x2c v = {lo, hi}; return __builtin_bit_cast(unsigned, __builtin_convertvector(v, bf16x2c)); }
; __device__ __forceinline__ float fma_s(float a, float b, float c) { float d; asm("v_fma_f32 %0, %1, %2, %3" : "=v"(d) : "v"(a), "v"(b), "v"(c)); return d; }
; #define PG8_ROR1(x) dpp_ror1(x)
; #define PG8_ROR15(x) dpp_ror15(x)
;     __device__ __forceinline__ void run(f32x4 (&acc)[2][2][4][2], const Unit& un, int wr, int wc, int fr, int fq, PG8_LAS unsigned char* xl) const {
;     ...
;                 for (int m = 0; m < 4; ++m) {
;                     float o[4];
; #pragma unroll
;                     for (int e = 0; e < 4; ++e) {
;                         const float g = acc[ai][0][m][n][e], v = acc[ai][1][m][n][e];
;                         const float gpe = m > 0 ? PG8_ROR1(acc[ai][0][m - 1][n][e]) : hpg[e], vpe = m > 0 ? PG8_ROR1(acc[ai][1][m - 1][n][e]) : hpv[e];
;                         const float gne = m < 3 ? PG8_ROR15(acc[ai][0][m + 1][n][e]) : hng[e], vne = m < 3 ? PG8_ROR15(acc[ai][1][m + 1][n][e]) : hnv[e];
;                         const float gpi = PG8_ROR1(g), vpi = PG8_ROR1(v), gni = PG8_ROR15(g), vni = PG8_ROR15(v);
;                         const float gp = e0 ? gpe : gpi, vp = e0 ? vpe : vpi, gn = e15 ? gne : gni, vn = e15 ? vne : vni;
;                         const float cg = fma_s(w2g[e], gn, fma_s(w1g[e], g, fma_s(w0g[e], gp, bg[e]))), cv = fma_s(w2v[e], vn, fma_s(w1v[e], v, fma_s(w0v[e], vp, bv[e])));
;                         o[e] = (cg * cv) * __builtin_amdgcn_rcpf(1.0f + __builtin_amdgcn_exp2f(cg * -1.4426950408889634f));
;                     }
;                     if (n == 0) { keep[m].x = cvt_pk_bf16(o[0], o[1]); keep[m].y = cvt_pk_bf16(o[2], o[3]); }
;                     else { u32x4 w; w.x = keep[m].x; w.y = keep[m].y; w.z = cvt_pk_bf16(o[0], o[1]); w.w = cvt_pk_bf16(o[2], o[3]);
;                         *(PG8_GAS u32x4*)(act + (size_t)(row0 + ai * HALF + m * 16) * dff + j - 4) = w; }
	v_add_f32_e32 v91, 1.0, v91
	v_rcp_f32_e32 v91, v91
	v_fmac_f32_dpp v250, v87, v125 row_shl:1 row_mask:0xf bank_mask:0xf
	v_fmac_f32_dpp v181, v72, v124 row_shr:15 row_mask:0xf bank_mask:0xf
	v_fmac_f32_dpp v248, v79, v105 row_shl:1 row_mask:0xf bank_mask:0xf
	v_fmac_f32_dpp v250, v77, v125 row_shr:15 row_mask:0xf bank_mask:0xf
	v_fmac_f32_dpp v251, v77, v113 row_shr:1 row_mask:0xf bank_mask:0xf
	v_fmac_f32_dpp v248, v69, v105 row_shr:15 row_mask:0xf bank_mask:0xf
	v_fmac_f32_dpp v255, v68, v100 row_shr:1 row_mask:0xf bank_mask:0xf
	v_fmac_f32_dpp v251, v87, v113 row_shl:15 row_mask:0xf bank_mask:0xf
	v_mov_b32_e32 v87, v250
	v_pk_mul_f32 v[86:87], v[88:89], v[86:87]
	v_pk_mul_f32 v[86:87], v[86:87], v[90:91]
	v_cvt_pk_bf16_f32 v145, v86, v87
	global_store_dwordx4 v[84:85], v[142:145], off
	v_fmac_f32_dpp v251, v77, v125 row_shl:1 row_mask:0xf bank_mask:0xf
	v_fmac_f32_dpp v255, v78, v100 row_shl:15 row_mask:0xf bank_mask:0xf
	v_mov_b32_e32 v78, v253
	v_fma_f32 v179, v106, v80, v118
	v_fma_f32 v185, v106, v66, v118
	v_fmac_f32_dpp v251, v73, v125 row_shr:15 row_mask:0xf bank_mask:0xf
	v_fmac_f32_dpp v179, v80, v98 row_shr:1 row_mask:0xf bank_mask:0xf
	v_fmac_f32_dpp v185, v66, v98 row_shr:1 row_mask:0xf bank_mask:0xf
	v_fmac_f32_dpp v255, v68, v104 row_shl:1 row_mask:0xf bank_mask:0xf
	v_fmac_f32_dpp v179, v168, v98 row_shl:15 row_mask:0xf bank_mask:0xf
	v_fmac_f32_dpp v185, v80, v98 row_shl:15 row_mask:0xf bank_mask:0xf
	v_fmac_f32_dpp v255, v136, v104 row_shr:15 row_mask:0xf bank_mask:0xf
	v_fmac_f32_dpp v179, v80, v102 row_shl:1 row_mask:0xf bank_mask:0xf
	v_fmac_f32_dpp v185, v66, v102 row_shl:1 row_mask:0xf bank_mask:0xf
	v_mov_b32_e32 v68, v255
	v_fmac_f32_dpp v179, v66, v102 row_shr:15 row_mask:0xf bank_mask:0xf
	v_mov_b32_e32 v80, v179
	v_fma_f32 v250, v114, v82, v126
	v_fma_f32 v253, v114, v70, v126
	v_mul_f32_e32 v84, 0xbfb8aa3b, v80
	v_fmac_f32_dpp v250, v82, v110 row_shr:1 row_mask:0xf bank_mask:0xf
	v_exp_f32_e32 v84, v84
	v_fmac_f32_dpp v185, v134, v102 row_shr:15 row_mask:0xf bank_mask:0xf
	v_fmac_f32_dpp v250, v170, v110 row_shl:15 row_mask:0xf bank_mask:0xf
	v_add_f32_e32 v84, 1.0, v84
	v_rcp_f32_e32 v84, v84
	v_fmac_f32_dpp v250, v82, v122 row_shl:1 row_mask:0xf bank_mask:0xf
	v_mov_b32_e32 v66, v185
	v_fmac_f32_dpp v253, v70, v110 row_shr:1 row_mask:0xf bank_mask:0xf
	v_fmac_f32_dpp v250, v70, v122 row_shr:15 row_mask:0xf bank_mask:0xf
	v_fmac_f32_dpp v183, v72, v112 row_shr:1 row_mask:0xf bank_mask:0xf
	v_fmac_f32_dpp v253, v82, v110 row_shl:15 row_mask:0xf bank_mask:0xf
	v_mov_b32_e32 v82, v250
	v_fma_f32 v255, v107, v81, v119
	v_fma_f32 v179, v107, v67, v119
	v_fmac_f32_dpp v253, v70, v122 row_shl:1 row_mask:0xf bank_mask:0xf
	v_fmac_f32_dpp v255, v81, v99 row_shr:1 row_mask:0xf bank_mask:0xf
	v_fmac_f32_dpp v179, v67, v99 row_shr:1 row_mask:0xf bank_mask:0xf
	v_fmac_f32_dpp v253, v130, v122 row_shr:15 row_mask:0xf bank_mask:0xf
	v_fmac_f32_dpp v255, v169, v99 row_shl:15 row_mask:0xf bank_mask:0xf
	v_mov_b32_e32 v70, v253
	v_fmac_f32_dpp v179, v81, v99 row_shl:15 row_mask:0xf bank_mask:0xf
	v_fmac_f32_dpp v255, v81, v103 row_shl:1 row_mask:0xf bank_mask:0xf
	v_fmac_f32_dpp v183, v76, v112 row_shl:15 row_mask:0xf bank_mask:0xf
	v_mov_b32_e32 v76, v181
	v_fmac_f32_dpp v255, v67, v103 row_shr:15 row_mask:0xf bank_mask:0xf
	v_mov_b32_e32 v81, v255
	v_mul_f32_e32 v85, 0xbfb8aa3b, v81
	v_exp_f32_e32 v85, v85
	v_fma_f32 v185, v115, v83, v127
	v_fma_f32 v250, v115, v71, v127
	v_add_f32_e32 v85, 1.0, v85
	v_rcp_f32_e32 v85, v85
	v_fmac_f32_dpp v185, v83, v111 row_shr:1 row_mask:0xf bank_mask:0xf
	v_fmac_f32_dpp v179, v67, v103 row_shl:1 row_mask:0xf bank_mask:0xf
	v_fmac_f32_dpp v250, v71, v111 row_shr:1 row_mask:0xf bank_mask:0xf
; #define PG8_GAS __attribute__((address_space(1)))
; #define PG8_ROR1(x) dpp_ror1(x)
; #define PG8_ROR15(x) dpp_ror15(x)
;     __device__ __forceinline__ void run(f32x4 (&acc)[2][2][4][2], const Unit& un, int wr, int wc, int fr, int fq, PG8_LAS unsigned char* xl) const {
;     ...
;             for (int n = 0; n < 2; ++n) {
;                 const int j = un.pn * 128 + cl + 4 * n;
;                 const f32x4 w0g = *(const PG8_GAS f32x4*)(cw + j), w1g = *(const PG8_GAS f32x4*)(cw + nup + j), w2g = *(const PG8_GAS f32x4*)(cw + 2 * (size_t)nup + j), bg = *(const PG8_GAS f32x4*)(cb + j);
;                 const f32x4 w0v = *(const PG8_GAS f32x4*)(cw + dff + j), w1v = *(const PG8_GAS f32x4*)(cw + nup + dff + j), w2v = *(const PG8_GAS f32x4*)(cw + 2 * (size_t)nup + dff + j), bv = *(const PG8_GAS f32x4*)(cb + dff + j);
;                 f32x4 hpg, hpv, hng, hnv;
;     ...
;                 for (int m = 0; m < 4; ++m) {
;                     float o[4];
; #pragma unroll
;                     for (int e = 0; e < 4; ++e) {
;                         const float g = acc[ai][0][m][n][e], v = acc[ai][1][m][n][e];
;                         const float gpe = m > 0 ? PG8_ROR1(acc[ai][0][m - 1][n][e]) : hpg[e], vpe = m > 0 ? PG8_ROR1(acc[ai][1][m - 1][n][e]) : hpv[e];
;                         const float gne = m < 3 ? PG8_ROR15(acc[ai][0][m + 1][n][e]) : hng[e], vne = m < 3 ? PG8_ROR15(acc[ai][1][m + 1][n][e]) : hnv[e];
;                         const float gpi = PG8_ROR1(g), vpi = PG8_ROR1(v), gni = PG8_ROR15(g), vni = PG8_ROR15(v);
;                         const float gp = e0 ? gpe : gpi, vp = e0 ? vpe : vpi, gn = e15 ? gne : gni, vn = e15 ? vne : vni;
;                         const float cg = fma_s(w2g[e], gn, fma_s(w1g[e], g, fma_s(w0g[e], gp, bg[e]))), cv = fma_s(w2v[e], vn, fma_s(w1v[e], v, fma_s(w0v[e], vp, bv[e])));
;                         o[e] = (cg * cv) * __builtin_amdgcn_rcpf(1.0f + __builtin_amdgcn_exp2f(cg * -1.4426950408889634f));
;                     }
;                     if (n == 0) { keep[m].x = cvt_pk_bf16(o[0], o[1]); keep[m].y = cvt_pk_bf16(o[2], o[3]); }
;                     else { u32x4 w; w.x = keep[m].x; w.y = keep[m].y; w.z = cvt_pk_bf16(o[0], o[1]); w.w = cvt_pk_bf16(o[2], o[3]);
;                         *(PG8_GAS u32x4*)(act + (size_t)(row0 + ai * HALF + m * 16) * dff + j - 4) = w; }
	v_fmac_f32_dpp v185, v171, v111 row_shl:15 row_mask:0xf bank_mask:0xf
	v_fmac_f32_dpp v179, v135, v103 row_shr:15 row_mask:0xf bank_mask:0xf
	v_mov_b32_e32 v67, v179
	v_fmac_f32_dpp v185, v83, v123 row_shl:1 row_mask:0xf bank_mask:0xf
	v_fmac_f32_dpp v250, v83, v111 row_shl:15 row_mask:0xf bank_mask:0xf
	v_fmac_f32_dpp v183, v72, v124 row_shl:1 row_mask:0xf bank_mask:0xf
	v_fmac_f32_dpp v185, v71, v123 row_shr:15 row_mask:0xf bank_mask:0xf
	v_mov_b32_e32 v83, v185
	v_pk_mul_f32 v[80:81], v[80:81], v[82:83]
	v_pk_mul_f32 v[80:81], v[80:81], v[84:85]
	v_mul_f32_e32 v82, 0xbfb8aa3b, v78
	v_exp_f32_e32 v82, v82
	v_cvt_pk_bf16_f32 v142, v80, v81
	v_add_f32_e32 v82, 1.0, v82
	v_rcp_f32_e32 v82, v82
	v_fmac_f32_dpp v250, v71, v123 row_shl:1 row_mask:0xf bank_mask:0xf
	v_fmac_f32_dpp v183, v132, v124 row_shr:15 row_mask:0xf bank_mask:0xf
	v_fmac_f32_dpp v249, v69, v101 row_shr:1 row_mask:0xf bank_mask:0xf
	v_fmac_f32_dpp v250, v131, v123 row_shr:15 row_mask:0xf bank_mask:0xf
	v_mov_b32_e32 v71, v250
	v_fmac_f32_dpp v249, v79, v101 row_shl:15 row_mask:0xf bank_mask:0xf
	v_mov_b32_e32 v79, v248
	v_mul_f32_e32 v83, 0xbfb8aa3b, v79
	v_exp_f32_e32 v83, v83
	v_fmac_f32_dpp v249, v69, v105 row_shl:1 row_mask:0xf bank_mask:0xf
	v_add_f32_e32 v83, 1.0, v83
	v_rcp_f32_e32 v83, v83
	v_fmac_f32_dpp v249, v137, v105 row_shr:15 row_mask:0xf bank_mask:0xf
	v_mov_b32_e32 v69, v249
	v_fmac_f32_dpp v252, v73, v113 row_shr:1 row_mask:0xf bank_mask:0xf
	s_nop 0
	s_nop 0
	v_fmac_f32_dpp v252, v77, v113 row_shl:15 row_mask:0xf bank_mask:0xf
	v_mov_b32_e32 v77, v251
	v_pk_mul_f32 v[76:77], v[78:79], v[76:77]
	v_pk_mul_f32 v[76:77], v[76:77], v[82:83]
	v_cvt_pk_bf16_f32 v143, v76, v77
	v_add_u32_e32 v76, 32, v172
	v_mad_i64_i32 v[76:77], s[14:15], v76, s5, v[74:75]
	v_lshl_add_u64 v[76:77], v[76:77], 0, v[146:147]
	global_store_dwordx4 v[76:77], v[140:143], off
	v_mul_f32_e32 v76, 0xbfb8aa3b, v66
	v_exp_f32_e32 v76, v76
	v_mul_f32_e32 v77, 0xbfb8aa3b, v67
	v_exp_f32_e32 v77, v77
	v_add_f32_e32 v76, 1.0, v76
	v_rcp_f32_e32 v76, v76
	v_add_f32_e32 v77, 1.0, v77
	v_rcp_f32_e32 v77, v77
	v_pk_mul_f32 v[66:67], v[66:67], v[70:71]
	v_pk_mul_f32 v[66:67], v[66:67], v[76:77]
	v_mul_f32_e32 v71, 0xbfb8aa3b, v68
	v_exp_f32_e32 v71, v71
	v_mov_b32_e32 v70, v183
	v_add_f32_e32 v71, 1.0, v71
	v_rcp_f32_e32 v72, v71
	v_cvt_pk_bf16_f32 v140, v66, v67
	v_fmac_f32_dpp v252, v73, v125 row_shl:1 row_mask:0xf bank_mask:0xf
	v_mul_f32_e32 v73, 0xbfb8aa3b, v69
	v_exp_f32_e32 v73, v73
	v_fmac_f32_dpp v252, v133, v125 row_shr:15 row_mask:0xf bank_mask:0xf
	v_mov_b32_e32 v71, v252
	v_add_u32_e32 v66, 48, v172
	v_pk_mul_f32 v[68:69], v[68:69], v[70:71]
	v_add_f32_e32 v73, 1.0, v73
	v_rcp_f32_e32 v73, v73
	v_mad_i64_i32 v[66:67], s[14:15], v66, s5, v[74:75]
	v_lshl_add_u64 v[66:67], v[66:67], 0, v[146:147]
	v_pk_mul_f32 v[68:69], v[68:69], v[72:73]
	v_cvt_pk_bf16_f32 v141, v68, v69
	global_store_dwordx4 v[66:67], v[138:141], off
	ds_read_b128 v[86:89], v247 offset:0
	ds_read_b128 v[82:85], v247 offset:512
	ds_read_b128 v[78:81], v247 offset:1024
	ds_read_b128 v[94:97], v247 offset:3072
	ds_read_b128 v[74:77], v247 offset:1536
	ds_read_b128 v[70:73], v247 offset:2048
	ds_read_b128 v[66:69], v247 offset:2560
	ds_read_b128 v[90:93], v247 offset:3584
	v_cndmask_b32_e64 v99, 0, 1, s[44:45]
	v_add_u32_e32 v115, s92, v197
	v_add_u32_e32 v117, s93, v197
	v_mov_b32_e32 v98, 0
	v_cmp_ne_u32_e64 s[14:15], 1, v99
	s_andn2_b64 vcc, exec, s[44:45]
	v_mov_b32_e32 v106, 0
	v_mov_b32_e32 v107, 0
	v_mov_b32_e32 v108, 0
	v_mov_b32_e32 v109, 0
	v_mov_b32_e32 v110, 0
	v_mov_b32_e32 v111, 0
	v_mov_b32_e32 v112, 0
	v_mov_b32_e32 v113, 0
	s_cbranch_vccnz .LBB0_804
	ds_read_b128 v[110:113], v117
	ds_read_b128 v[106:109], v115

; __device__ __forceinline__ float fma_s(float a, float b, float c) { float d; asm("v_fma_f32 %0, %1, %2, %3" : "=v"(d) : "v"(a), "v"(b), "v"(c)); return d; }
; #define PG8_ROR1(x) dpp_ror1(x)
; #define PG8_ROR15(x) dpp_ror15(x)
;     __device__ __forceinline__ void run(f32x4 (&acc)[2][2][4][2], const Unit& un, int wr, int wc, int fr, int fq, PG8_LAS unsigned char* xl) const {
;     ...
;             for (int m = 0; m < 4; ++m) { const float iv = __builtin_amdgcn_rsqf(ssq[(size_t)un.pm * BM + wr * 64 + fr + ai * HALF + m * 16] * inv_n + eps);
; #pragma unroll
;                 for (int bj = 0; bj < 2; ++bj)
; #pragma unroll
;                     for (int n = 0; n < 2; ++n) acc[ai][bj][m][n] = acc[ai][bj][m][n] * iv; }
;     ...
;                     for (int e = 0; e < 4; ++e) {
;                         const float g = acc[ai][0][m][n][e], v = acc[ai][1][m][n][e];
;                         const float gpe = m > 0 ? PG8_ROR1(acc[ai][0][m - 1][n][e]) : hpg[e], vpe = m > 0 ? PG8_ROR1(acc[ai][1][m - 1][n][e]) : hpv[e];
;                         const float gne = m < 3 ? PG8_ROR15(acc[ai][0][m + 1][n][e]) : hng[e], vne = m < 3 ? PG8_ROR15(acc[ai][1][m + 1][n][e]) : hnv[e];
;                         const float gpi = PG8_ROR1(g), vpi = PG8_ROR1(v), gni = PG8_ROR15(g), vni = PG8_ROR15(v);
;                         const float gp = e0 ? gpe : gpi, vp = e0 ? vpe : vpi, gn = e15 ? gne : gni, vn = e15 ? vne : vni;
;                         const float cg = fma_s(w2g[e], gn, fma_s(w1g[e], g, fma_s(w0g[e], gp, bg[e]))), cv = fma_s(w2v[e], vn, fma_s(w1v[e], v, fma_s(w0v[e], vp, bv[e])));
;                         o[e] = (cg * cv) * __builtin_amdgcn_rcpf(1.0f + __builtin_amdgcn_exp2f(cg * -1.4426950408889634f));
.LBB0_806:
	v_fmamk_f32 v114, v245, 0x39800000, v244
	v_fmamk_f32 v116, v211, 0x39800000, v244
	v_rsq_f32_e32 v114, v114
	v_rsq_f32_e32 v116, v116
	v_pk_mul_f32 v[124:125], v[32:33], v[114:115] op_sel_hi:[1,0]
	v_pk_mul_f32 v[32:33], v[34:35], v[116:117] op_sel_hi:[1,0]
	s_waitcnt lgkmcnt(1)
	v_pk_mul_f32 v[42:43], v[42:43], v[114:115] op_sel_hi:[1,0]
	s_waitcnt lgkmcnt(0)
	v_pk_mul_f32 v[120:121], v[30:31], v[114:115] op_sel_hi:[1,0]
	v_pk_mul_f32 v[30:31], v[36:37], v[116:117] op_sel_hi:[1,0]
	s_waitcnt lgkmcnt(0)
	v_fma_f32 v253, v82, v58, v94
	s_waitcnt lgkmcnt(0)
	v_fma_f32 v181, v70, v62, v90
	v_fmac_f32_dpp v253, v58, v86 row_shr:1 row_mask:0xf bank_mask:0xf
	v_fma_f32 v255, v83, v59, v95
	v_fma_f32 v179, v71, v63, v91
	v_fmac_f32_dpp v253, v110, v86 row_shl:15 row_mask:0xf bank_mask:0xf
	v_fmac_f32_dpp v181, v62, v74 row_shr:1 row_mask:0xf bank_mask:0xf
	v_fmac_f32_dpp v255, v59, v87 row_shr:1 row_mask:0xf bank_mask:0xf
	v_fmac_f32_dpp v253, v58, v78 row_shl:1 row_mask:0xf bank_mask:0xf
	v_fmac_f32_dpp v181, v106, v74 row_shl:15 row_mask:0xf bank_mask:0xf
	v_fmac_f32_dpp v255, v111, v87 row_shl:15 row_mask:0xf bank_mask:0xf
	v_fmac_f32_dpp v253, v42, v78 row_shr:15 row_mask:0xf bank_mask:0xf
	v_mov_b32_e32 v106, v253
	v_fmac_f32_dpp v181, v62, v66 row_shl:1 row_mask:0xf bank_mask:0xf
	v_fmac_f32_dpp v255, v59, v79 row_shl:1 row_mask:0xf bank_mask:0xf
	v_fmac_f32_dpp v179, v63, v75 row_shr:1 row_mask:0xf bank_mask:0xf
	v_fmac_f32_dpp v181, v120, v66 row_shr:15 row_mask:0xf bank_mask:0xf
	v_mov_b32_e32 v110, v181
	v_fmac_f32_dpp v255, v43, v79 row_shr:15 row_mask:0xf bank_mask:0xf
	v_fmac_f32_dpp v179, v107, v75 row_shl:15 row_mask:0xf bank_mask:0xf
	v_mov_b32_e32 v107, v255
	v_pk_mul_f32 v[44:45], v[44:45], v[114:115] op_sel_hi:[1,0]
	v_fmac_f32_dpp v179, v63, v67 row_shl:1 row_mask:0xf bank_mask:0xf
	v_fma_f32 v185, v84, v60, v96
	v_fma_f32 v250, v72, v64, v92
	v_fmac_f32_dpp v179, v121, v67 row_shr:15 row_mask:0xf bank_mask:0xf
	v_mov_b32_e32 v111, v179
	v_fmac_f32_dpp v185, v60, v88 row_shr:1 row_mask:0xf bank_mask:0xf
	v_fmac_f32_dpp v250, v64, v76 row_shr:1 row_mask:0xf bank_mask:0xf
	v_fma_f32 v248, v85, v61, v97
	v_fma_f32 v249, v73, v65, v93
	v_fmac_f32_dpp v185, v112, v88 row_shl:15 row_mask:0xf bank_mask:0xf
	v_fmac_f32_dpp v250, v108, v76 row_shl:15 row_mask:0xf bank_mask:0xf
	v_fmac_f32_dpp v248, v61, v89 row_shr:1 row_mask:0xf bank_mask:0xf
	v_fmac_f32_dpp v185, v60, v80 row_shl:1 row_mask:0xf bank_mask:0xf
	v_fmac_f32_dpp v250, v64, v68 row_shl:1 row_mask:0xf bank_mask:0xf
	v_fmac_f32_dpp v248, v113, v89 row_shl:15 row_mask:0xf bank_mask:0xf
	v_fmac_f32_dpp v185, v44, v80 row_shr:15 row_mask:0xf bank_mask:0xf
	v_mov_b32_e32 v108, v185
	v_fmac_f32_dpp v250, v124, v68 row_shr:15 row_mask:0xf bank_mask:0xf
	v_mov_b32_e32 v112, v250
	v_fmac_f32_dpp v248, v61, v81 row_shl:1 row_mask:0xf bank_mask:0xf
	v_fmac_f32_dpp v249, v65, v77 row_shr:1 row_mask:0xf bank_mask:0xf
	v_pk_mul_f32 v[26:27], v[26:27], v[116:117] op_sel_hi:[1,0]
	v_fmac_f32_dpp v248, v45, v81 row_shr:15 row_mask:0xf bank_mask:0xf
	v_fmac_f32_dpp v249, v109, v77 row_shl:15 row_mask:0xf bank_mask:0xf
	v_mov_b32_e32 v109, v248
	v_fma_f32 v118, v82, v42, v94
	v_fmac_f32_dpp v249, v65, v69 row_shl:1 row_mask:0xf bank_mask:0xf
	v_fma_f32 v251, v70, v120, v90
	v_fma_f32 v128, v70, v26, v90
	v_fmac_f32_dpp v249, v125, v69 row_shr:15 row_mask:0xf bank_mask:0xf
	v_mov_b32_e32 v113, v249
	v_fmac_f32_dpp v118, v42, v86 row_shr:1 row_mask:0xf bank_mask:0xf
	v_fmac_f32_dpp v251, v120, v74 row_shr:1 row_mask:0xf bank_mask:0xf
	v_fma_f32 v119, v83, v43, v95
	v_fmac_f32_dpp v118, v58, v86 row_shl:15 row_mask:0xf bank_mask:0xf
	v_fmac_f32_dpp v251, v62, v74 row_shl:15 row_mask:0xf bank_mask:0xf
	v_fmac_f32_dpp v119, v43, v87 row_shr:1 row_mask:0xf bank_mask:0xf
	v_fmac_f32_dpp v118, v42, v78 row_shl:1 row_mask:0xf bank_mask:0xf
	v_fmac_f32_dpp v251, v120, v66 row_shl:1 row_mask:0xf bank_mask:0xf
	v_fmac_f32_dpp v119, v59, v87 row_shl:15 row_mask:0xf bank_mask:0xf
	v_fmac_f32_dpp v118, v32, v78 row_shr:15 row_mask:0xf bank_mask:0xf
	v_fmac_f32_dpp v251, v26, v66 row_shr:15 row_mask:0xf bank_mask:0xf
	v_fmac_f32_dpp v119, v43, v79 row_shl:1 row_mask:0xf bank_mask:0xf
	v_fma_f32 v183, v71, v121, v91
	v_fma_f32 v129, v71, v27, v91
	v_fmac_f32_dpp v119, v33, v79 row_shr:15 row_mask:0xf bank_mask:0xf
	v_fmac_f32_dpp v183, v121, v75 row_shr:1 row_mask:0xf bank_mask:0xf
	v_pk_mul_f32 v[28:29], v[28:29], v[116:117] op_sel_hi:[1,0]
	v_fma_f32 v122, v84, v44, v96
	v_fmac_f32_dpp v183, v63, v75 row_shl:15 row_mask:0xf bank_mask:0xf
	v_fma_f32 v252, v72, v124, v92
	v_fma_f32 v132, v72, v28, v92
	v_fmac_f32_dpp v183, v121, v67 row_shl:1 row_mask:0xf bank_mask:0xf
	v_fmac_f32_dpp v122, v44, v88 row_shr:1 row_mask:0xf bank_mask:0xf
	v_fmac_f32_dpp v252, v124, v76 row_shr:1 row_mask:0xf bank_mask:0xf
	v_fmac_f32_dpp v183, v27, v67 row_shr:15 row_mask:0xf bank_mask:0xf
	v_fmac_f32_dpp v122, v60, v88 row_shl:15 row_mask:0xf bank_mask:0xf
	v_fmac_f32_dpp v252, v64, v76 row_shl:15 row_mask:0xf bank_mask:0xf
	v_fma_f32 v123, v85, v45, v97
	v_fmac_f32_dpp v122, v44, v80 row_shl:1 row_mask:0xf bank_mask:0xf
	v_fmac_f32_dpp v252, v124, v68 row_shl:1 row_mask:0xf bank_mask:0xf
	v_fmac_f32_dpp v123, v45, v89 row_shr:1 row_mask:0xf bank_mask:0xf
	v_fmac_f32_dpp v122, v30, v80 row_shr:15 row_mask:0xf bank_mask:0xf
	v_fmac_f32_dpp v252, v28, v68 row_shr:15 row_mask:0xf bank_mask:0xf
	v_fmac_f32_dpp v123, v61, v89 row_shl:15 row_mask:0xf bank_mask:0xf
	v_fma_f32 v253, v73, v125, v93
	v_fma_f32 v133, v73, v29, v93
	v_fmac_f32_dpp v123, v45, v81 row_shl:1 row_mask:0xf bank_mask:0xf
; #define PG8_LAS __attribute__((address_space(3)))
; #define PG8_GAS __attribute__((address_space(1)))
; __device__ __forceinline__ float fma_s(float a, float b, float c) { float d; asm("v_fma_f32 %0, %1, %2, %3" : "=v"(d) : "v"(a), "v"(b), "v"(c)); return d; }
; #define PG8_ROR1(x) dpp_ror1(x)
;     __device__ __forceinline__ void run(f32x4 (&acc)[2][2][4][2], const Unit& un, int wr, int wc, int fr, int fq, PG8_LAS unsigned char* xl) const {
;     ...
;             for (int n = 0; n < 2; ++n) {
;                 const int j = un.pn * 128 + cl + 4 * n;
;                 const f32x4 w0g = *(const PG8_GAS f32x4*)(cw + j), w1g = *(const PG8_GAS f32x4*)(cw + nup + j), w2g = *(const PG8_GAS f32x4*)(cw + 2 * (size_t)nup + j), bg = *(const PG8_GAS f32x4*)(cb + j);
;                 const f32x4 w0v = *(const PG8_GAS f32x4*)(cw + dff + j), w1v = *(const PG8_GAS f32x4*)(cw + nup + dff + j), w2v = *(const PG8_GAS f32x4*)(cw + 2 * (size_t)nup + dff + j), bv = *(const PG8_GAS f32x4*)(cb + dff + j);
;                 f32x4 hpg, hpv, hng, hnv;
;                 if (blk > 0) { hpg = *(const PG8_LAS f32x4*)(X + ((blk - 1) * 2 + 1) * 256 + cl + 4 * n); hpv = *(const PG8_LAS f32x4*)(X + ((blk - 1) * 2 + 1) * 256 + 128 + cl + 4 * n); } else { hpg = (f32x4){0.f, 0.f, 0.f, 0.f}; hpv = hpg; }
;                 if (blk < 3) { hng = *(const PG8_LAS f32x4*)(X + ((blk + 1) * 2 + 0) * 256 + cl + 4 * n); hnv = *(const PG8_LAS f32x4*)(X + ((blk + 1) * 2 + 0) * 256 + 128 + cl + 4 * n); } else { hng = (f32x4){0.f, 0.f, 0.f, 0.f}; hnv = hng; }
;     ...
;                     for (int e = 0; e < 4; ++e) {
;                         const float g = acc[ai][0][m][n][e], v = acc[ai][1][m][n][e];
;                         const float gpe = m > 0 ? PG8_ROR1(acc[ai][0][m - 1][n][e]) : hpg[e], vpe = m > 0 ? PG8_ROR1(acc[ai][1][m - 1][n][e]) : hpv[e];
;                         const float gne = m < 3 ? PG8_ROR15(acc[ai][0][m + 1][n][e]) : hng[e], vne = m < 3 ? PG8_ROR15(acc[ai][1][m + 1][n][e]) : hnv[e];
;                         const float gpi = PG8_ROR1(g), vpi = PG8_ROR1(v), gni = PG8_ROR15(g), vni = PG8_ROR15(v);
;                         const float gp = e0 ? gpe : gpi, vp = e0 ? vpe : vpi, gn = e15 ? gne : gni, vn = e15 ? vne : vni;
;                         const float cg = fma_s(w2g[e], gn, fma_s(w1g[e], g, fma_s(w0g[e], gp, bg[e]))), cv = fma_s(w2v[e], vn, fma_s(w1v[e], v, fma_s(w0v[e], vp, bv[e])));
	v_fmac_f32_dpp v253, v125, v77 row_shr:1 row_mask:0xf bank_mask:0xf
	v_fma_f32 v126, v82, v32, v94
	v_fmac_f32_dpp v123, v31, v81 row_shr:15 row_mask:0xf bank_mask:0xf
	v_fmac_f32_dpp v253, v65, v77 row_shl:15 row_mask:0xf bank_mask:0xf
	v_fmac_f32_dpp v126, v32, v86 row_shr:1 row_mask:0xf bank_mask:0xf
	v_fmac_f32_dpp v128, v26, v74 row_shr:1 row_mask:0xf bank_mask:0xf
	v_fmac_f32_dpp v253, v125, v69 row_shl:1 row_mask:0xf bank_mask:0xf
	v_fmac_f32_dpp v126, v42, v86 row_shl:15 row_mask:0xf bank_mask:0xf
	v_fmac_f32_dpp v128, v120, v74 row_shl:15 row_mask:0xf bank_mask:0xf
	v_mov_b32_e32 v120, v251
	v_fmac_f32_dpp v253, v29, v69 row_shr:15 row_mask:0xf bank_mask:0xf
	v_fmac_f32_dpp v126, v32, v78 row_shl:1 row_mask:0xf bank_mask:0xf
	v_fmac_f32_dpp v128, v26, v66 row_shl:1 row_mask:0xf bank_mask:0xf
	v_fma_f32 v127, v83, v33, v95
	v_fmac_f32_dpp v126, v50, v78 row_shr:15 row_mask:0xf bank_mask:0xf
	v_fmac_f32_dpp v128, v54, v66 row_shr:15 row_mask:0xf bank_mask:0xf
	v_fmac_f32_dpp v127, v33, v87 row_shr:1 row_mask:0xf bank_mask:0xf
	v_fmac_f32_dpp v129, v27, v75 row_shr:1 row_mask:0xf bank_mask:0xf
	v_fma_f32 v130, v84, v30, v96
	v_fmac_f32_dpp v127, v43, v87 row_shl:15 row_mask:0xf bank_mask:0xf
	v_fmac_f32_dpp v129, v121, v75 row_shl:15 row_mask:0xf bank_mask:0xf
	v_mov_b32_e32 v121, v183
	v_fmac_f32_dpp v127, v33, v79 row_shl:1 row_mask:0xf bank_mask:0xf
	v_fmac_f32_dpp v129, v27, v67 row_shl:1 row_mask:0xf bank_mask:0xf
	v_fmac_f32_dpp v130, v30, v88 row_shr:1 row_mask:0xf bank_mask:0xf
	v_fmac_f32_dpp v127, v51, v79 row_shr:15 row_mask:0xf bank_mask:0xf
	v_fmac_f32_dpp v129, v55, v67 row_shr:15 row_mask:0xf bank_mask:0xf
	v_fmac_f32_dpp v130, v44, v88 row_shl:15 row_mask:0xf bank_mask:0xf
	v_fmac_f32_dpp v132, v28, v76 row_shr:1 row_mask:0xf bank_mask:0xf
	v_fma_f32 v131, v85, v31, v97
	v_fmac_f32_dpp v130, v30, v80 row_shl:1 row_mask:0xf bank_mask:0xf
	v_fmac_f32_dpp v132, v124, v76 row_shl:15 row_mask:0xf bank_mask:0xf
	v_mov_b32_e32 v124, v252
	v_fmac_f32_dpp v130, v52, v80 row_shr:15 row_mask:0xf bank_mask:0xf
	v_fmac_f32_dpp v132, v28, v68 row_shl:1 row_mask:0xf bank_mask:0xf
	v_fmac_f32_dpp v131, v31, v89 row_shr:1 row_mask:0xf bank_mask:0xf
	v_fmac_f32_dpp v133, v29, v77 row_shr:1 row_mask:0xf bank_mask:0xf
	v_fmac_f32_dpp v132, v56, v68 row_shr:15 row_mask:0xf bank_mask:0xf
	v_fmac_f32_dpp v131, v45, v89 row_shl:15 row_mask:0xf bank_mask:0xf
	v_fmac_f32_dpp v133, v125, v77 row_shl:15 row_mask:0xf bank_mask:0xf
	v_mov_b32_e32 v125, v253
	v_fmac_f32_dpp v131, v31, v81 row_shl:1 row_mask:0xf bank_mask:0xf
	v_fmac_f32_dpp v133, v29, v69 row_shl:1 row_mask:0xf bank_mask:0xf
	v_fma_f32 v94, v82, v50, v94
	v_fmac_f32_dpp v131, v53, v81 row_shr:15 row_mask:0xf bank_mask:0xf
	v_fmac_f32_dpp v133, v57, v69 row_shr:15 row_mask:0xf bank_mask:0xf
	v_fmac_f32_dpp v94, v50, v86 row_shr:1 row_mask:0xf bank_mask:0xf
	v_fma_f32 v90, v70, v54, v90
	v_fma_f32 v95, v83, v51, v95
	v_fmac_f32_dpp v94, v32, v86 row_shl:15 row_mask:0xf bank_mask:0xf
	v_fmac_f32_dpp v90, v54, v74 row_shr:1 row_mask:0xf bank_mask:0xf
	v_fmac_f32_dpp v95, v51, v87 row_shr:1 row_mask:0xf bank_mask:0xf
	v_fmac_f32_dpp v94, v50, v78 row_shl:1 row_mask:0xf bank_mask:0xf
	v_fmac_f32_dpp v90, v26, v74 row_shl:15 row_mask:0xf bank_mask:0xf
	v_fmac_f32_dpp v95, v33, v87 row_shl:15 row_mask:0xf bank_mask:0xf
	v_fmac_f32_dpp v94, v102, v78 row_shr:15 row_mask:0xf bank_mask:0xf
	v_fmac_f32_dpp v90, v54, v66 row_shl:1 row_mask:0xf bank_mask:0xf
	v_fmac_f32_dpp v95, v51, v79 row_shl:1 row_mask:0xf bank_mask:0xf
	v_fma_f32 v91, v71, v55, v91
	v_fmac_f32_dpp v90, v98, v66 row_shr:15 row_mask:0xf bank_mask:0xf
	v_fmac_f32_dpp v95, v103, v79 row_shr:15 row_mask:0xf bank_mask:0xf
	v_fmac_f32_dpp v91, v55, v75 row_shr:1 row_mask:0xf bank_mask:0xf
	v_fma_f32 v181, v84, v52, v96
	v_fma_f32 v92, v72, v56, v92
	v_fmac_f32_dpp v91, v27, v75 row_shl:15 row_mask:0xf bank_mask:0xf
	v_fmac_f32_dpp v181, v52, v88 row_shr:1 row_mask:0xf bank_mask:0xf
	v_fmac_f32_dpp v92, v56, v76 row_shr:1 row_mask:0xf bank_mask:0xf
	v_fmac_f32_dpp v91, v55, v67 row_shl:1 row_mask:0xf bank_mask:0xf
	v_fmac_f32_dpp v181, v30, v88 row_shl:15 row_mask:0xf bank_mask:0xf
	v_fmac_f32_dpp v92, v28, v76 row_shl:15 row_mask:0xf bank_mask:0xf
	v_fmac_f32_dpp v91, v99, v67 row_shr:15 row_mask:0xf bank_mask:0xf
	v_fmac_f32_dpp v181, v52, v80 row_shl:1 row_mask:0xf bank_mask:0xf
	v_fmac_f32_dpp v92, v56, v68 row_shl:1 row_mask:0xf bank_mask:0xf
	v_fma_f32 v255, v85, v53, v97
	v_fmac_f32_dpp v181, v104, v80 row_shr:15 row_mask:0xf bank_mask:0xf
	v_mov_b32_e32 v88, v181
	v_fmac_f32_dpp v92, v100, v68 row_shr:15 row_mask:0xf bank_mask:0xf
	v_fmac_f32_dpp v255, v53, v89 row_shr:1 row_mask:0xf bank_mask:0xf
	v_fma_f32 v93, v73, v57, v93
	ds_read_b128 v[62:65], v247 offset:16
	v_fmac_f32_dpp v255, v31, v89 row_shl:15 row_mask:0xf bank_mask:0xf
	v_fmac_f32_dpp v93, v57, v77 row_shr:1 row_mask:0xf bank_mask:0xf
	ds_read_b128 v[58:61], v247 offset:528
	v_fmac_f32_dpp v255, v53, v81 row_shl:1 row_mask:0xf bank_mask:0xf
	v_fmac_f32_dpp v93, v29, v77 row_shl:15 row_mask:0xf bank_mask:0xf
	v_mov_b32_e32 v50, 0
	v_fmac_f32_dpp v255, v105, v81 row_shr:15 row_mask:0xf bank_mask:0xf
	v_mov_b32_e32 v89, v255
	v_fmac_f32_dpp v93, v57, v69 row_shl:1 row_mask:0xf bank_mask:0xf
	ds_read_b128 v[54:57], v247 offset:1040
	v_mov_b32_e32 v74, 0
	v_fmac_f32_dpp v93, v101, v69 row_shr:15 row_mask:0xf bank_mask:0xf
	ds_read_b128 v[66:69], v247 offset:3088
	ds_read_b128 v[34:37], v247 offset:1552
	ds_read_b128 v[26:29], v247 offset:2064
	ds_read_b128 v[30:33], v247 offset:2576
	ds_read_b128 v[42:45], v247 offset:3600
	s_and_b64 vcc, exec, s[14:15]
	v_mov_b32_e32 v75, 0
	v_mov_b32_e32 v76, 0
	v_mov_b32_e32 v77, 0
	v_mov_b32_e32 v78, 0
	v_mov_b32_e32 v79, 0
	v_mov_b32_e32 v80, 0
	v_mov_b32_e32 v81, 0
	s_cbranch_vccnz .LBB0_808
	ds_read_b128 v[78:81], v117 offset:16
	ds_read_b128 v[74:77], v115 offset:16

; #define PG8_GAS __attribute__((address_space(1)))
; __device__ __forceinline__ unsigned cvt_pk_bf16(float lo, float hi) { const f32x2c v = {lo, hi}; return __builtin_bit_cast(unsigned, __builtin_convertvector(v, bf16x2c)); }
;     __device__ __forceinline__ void run(f32x4 (&acc)[2][2][4][2], const Unit& un, int wr, int wc, int fr, int fq, PG8_LAS unsigned char* xl) const {
;     ...
;             for (int m = 0; m < 4; ++m) { const float iv = __builtin_amdgcn_rsqf(ssq[(size_t)un.pm * BM + wr * 64 + fr + ai * HALF + m * 16] * inv_n + eps);
; #pragma unroll
;                 for (int bj = 0; bj < 2; ++bj)
; #pragma unroll
;                     for (int n = 0; n < 2; ++n) acc[ai][bj][m][n] = acc[ai][bj][m][n] * iv; }
;     ...
;                         o[e] = (cg * cv) * __builtin_amdgcn_rcpf(1.0f + __builtin_amdgcn_exp2f(cg * -1.4426950408889634f));
;                     }
;                     if (n == 0) { keep[m].x = cvt_pk_bf16(o[0], o[1]); keep[m].y = cvt_pk_bf16(o[2], o[3]); }
;                     else { u32x4 w; w.x = keep[m].x; w.y = keep[m].y; w.z = cvt_pk_bf16(o[0], o[1]); w.w = cvt_pk_bf16(o[2], o[3]);
;                         *(PG8_GAS u32x4*)(act + (size_t)(row0 + ai * HALF + m * 16) * dff + j - 4) = w; }
.LBB0_810:
	v_mov_b32_e32 v115, v114
	v_mov_b32_e32 v117, v116
	v_mov_b32_e32 v84, v114
	v_mov_b32_e32 v85, v114
	v_pk_mul_f32 v[82:83], v[16:17], v[84:85]
	v_pk_mul_f32 v[86:87], v[14:15], v[114:115]
	v_pk_mul_f32 v[8:9], v[8:9], v[84:85]
	v_pk_mul_f32 v[84:85], v[6:7], v[114:115]
	v_mov_b32_e32 v6, v116
	v_mov_b32_e32 v7, v116
	v_pk_mul_f32 v[14:15], v[2:3], v[116:117]
	v_mul_f32_e32 v2, 0xbfb8aa3b, v88
	v_pk_mul_f32 v[16:17], v[10:11], v[116:117]
	v_pk_mul_f32 v[10:11], v[4:5], v[6:7]
	v_exp_f32_e32 v4, v2
	v_mul_f32_e32 v2, 0xbfb8aa3b, v89
	v_pk_mul_f32 v[12:13], v[12:13], v[6:7]
	v_exp_f32_e32 v5, v2
	v_mul_f32_e32 v6, 0xbfb8aa3b, v94
	v_mul_f32_e32 v7, 0xbfb8aa3b, v95
	v_exp_f32_e32 v6, v6
	v_exp_f32_e32 v7, v7
	v_add_f32_e32 v4, 1.0, v4
	v_add_f32_e32 v5, 1.0, v5
	v_rcp_f32_e32 v4, v4
	v_rcp_f32_e32 v5, v5
	v_add_f32_e32 v6, 1.0, v6
	v_add_f32_e32 v7, 1.0, v7
	v_rcp_f32_e32 v6, v6
	v_rcp_f32_e32 v7, v7
	v_pk_mul_f32 v[2:3], v[88:89], v[92:93]
	v_mul_f32_e32 v88, 0xbfb8aa3b, v126
	v_pk_mul_f32 v[2:3], v[2:3], v[4:5]
	v_pk_mul_f32 v[4:5], v[94:95], v[90:91]
	v_cvt_pk_bf16_f32 v3, v2, v3
	v_pk_mul_f32 v[4:5], v[4:5], v[6:7]
	v_mul_f32_e32 v89, 0xbfb8aa3b, v127
	v_cvt_pk_bf16_f32 v2, v4, v5
	v_mul_f32_e32 v4, 0xbfb8aa3b, v130
	v_exp_f32_e32 v6, v4
	v_mul_f32_e32 v4, 0xbfb8aa3b, v131
	v_exp_f32_e32 v7, v4
	v_exp_f32_e32 v88, v88
	v_exp_f32_e32 v89, v89
	v_add_f32_e32 v6, 1.0, v6
	v_add_f32_e32 v7, 1.0, v7
	v_rcp_f32_e32 v6, v6
	v_rcp_f32_e32 v7, v7
	v_add_f32_e32 v88, 1.0, v88
	v_add_f32_e32 v89, 1.0, v89
	v_rcp_f32_e32 v88, v88
	v_rcp_f32_e32 v89, v89
	v_pk_mul_f32 v[4:5], v[130:131], v[132:133]
	v_mul_f32_e32 v90, 0xbfb8aa3b, v118
	v_pk_mul_f32 v[4:5], v[4:5], v[6:7]
	v_pk_mul_f32 v[6:7], v[126:127], v[128:129]
	v_cvt_pk_bf16_f32 v5, v4, v5
	v_pk_mul_f32 v[6:7], v[6:7], v[88:89]
	v_mul_f32_e32 v91, 0xbfb8aa3b, v119
	v_cvt_pk_bf16_f32 v4, v6, v7
	v_mul_f32_e32 v6, 0xbfb8aa3b, v122
	v_exp_f32_e32 v88, v6
	v_mul_f32_e32 v6, 0xbfb8aa3b, v123
	v_exp_f32_e32 v89, v6
	v_exp_f32_e32 v90, v90
	v_exp_f32_e32 v91, v91
	v_add_f32_e32 v88, 1.0, v88
	v_add_f32_e32 v89, 1.0, v89
	v_rcp_f32_e32 v88, v88
	v_rcp_f32_e32 v89, v89
	v_add_f32_e32 v90, 1.0, v90
	v_add_f32_e32 v91, 1.0, v91
	v_rcp_f32_e32 v90, v90
	v_rcp_f32_e32 v91, v91
	v_pk_mul_f32 v[6:7], v[122:123], v[124:125]
	v_mul_f32_e32 v92, 0xbfb8aa3b, v106
	v_pk_mul_f32 v[6:7], v[6:7], v[88:89]
	v_pk_mul_f32 v[88:89], v[118:119], v[120:121]
	v_cvt_pk_bf16_f32 v7, v6, v7
	v_pk_mul_f32 v[88:89], v[88:89], v[90:91]
	v_mul_f32_e32 v93, 0xbfb8aa3b, v107
	v_cvt_pk_bf16_f32 v6, v88, v89
	v_mul_f32_e32 v88, 0xbfb8aa3b, v108
	v_exp_f32_e32 v90, v88
	v_mul_f32_e32 v88, 0xbfb8aa3b, v109
	v_exp_f32_e32 v91, v88
	v_exp_f32_e32 v92, v92
	v_exp_f32_e32 v93, v93
	v_add_f32_e32 v90, 1.0, v90
	v_add_f32_e32 v91, 1.0, v91
	v_rcp_f32_e32 v90, v90
	v_rcp_f32_e32 v91, v91
	v_add_f32_e32 v92, 1.0, v92
	v_add_f32_e32 v93, 1.0, v93
	v_rcp_f32_e32 v92, v92
	v_rcp_f32_e32 v93, v93
	v_pk_mul_f32 v[88:89], v[108:109], v[112:113]
	v_pk_mul_f32 v[88:89], v[88:89], v[90:91]
	v_pk_mul_f32 v[90:91], v[106:107], v[110:111]
	v_cvt_pk_bf16_f32 v89, v88, v89
	v_pk_mul_f32 v[90:91], v[90:91], v[92:93]
	v_cvt_pk_bf16_f32 v88, v90, v91
	s_waitcnt lgkmcnt(1)
	s_waitcnt lgkmcnt(0)
	s_waitcnt lgkmcnt(0)
	v_fma_f32 v179, v58, v38, v66
	s_waitcnt lgkmcnt(0)
	v_fma_f32 v185, v26, v46, v42
	v_fmac_f32_dpp v179, v38, v62 row_shr:1 row_mask:0xf bank_mask:0xf
	v_fma_f32 v250, v59, v39, v67
	v_fma_f32 v248, v27, v47, v43
	v_fmac_f32_dpp v179, v78, v62 row_shl:15 row_mask:0xf bank_mask:0xf
	v_fmac_f32_dpp v185, v46, v34 row_shr:1 row_mask:0xf bank_mask:0xf
	v_fmac_f32_dpp v250, v39, v63 row_shr:1 row_mask:0xf bank_mask:0xf
	v_fmac_f32_dpp v179, v38, v54 row_shl:1 row_mask:0xf bank_mask:0xf
	v_fmac_f32_dpp v185, v74, v34 row_shl:15 row_mask:0xf bank_mask:0xf
	v_fmac_f32_dpp v250, v79, v63 row_shl:15 row_mask:0xf bank_mask:0xf
	v_fmac_f32_dpp v179, v86, v54 row_shr:15 row_mask:0xf bank_mask:0xf
	v_mov_b32_e32 v74, v179
	v_mul_f32_e32 v78, 0xbfb8aa3b, v74
	v_exp_f32_e32 v94, v78
	v_fmac_f32_dpp v185, v46, v30 row_shl:1 row_mask:0xf bank_mask:0xf
	v_add_f32_e32 v90, 1.0, v94
	v_rcp_f32_e32 v90, v90
	v_fmac_f32_dpp v185, v84, v30 row_shr:15 row_mask:0xf bank_mask:0xf
	v_mov_b32_e32 v78, v185
	v_fmac_f32_dpp v250, v39, v55 row_shl:1 row_mask:0xf bank_mask:0xf
	v_fmac_f32_dpp v248, v47, v35 row_shr:1 row_mask:0xf bank_mask:0xf
	v_fma_f32 v249, v60, v40, v68
	v_fma_f32 v251, v28, v48, v44
	v_fmac_f32_dpp v250, v87, v55 row_shr:15 row_mask:0xf bank_mask:0xf
	v_fmac_f32_dpp v248, v75, v35 row_shl:15 row_mask:0xf bank_mask:0xf
	v_mov_b32_e32 v75, v250
	v_mul_f32_e32 v79, 0xbfb8aa3b, v75
	v_exp_f32_e32 v79, v79
	v_fmac_f32_dpp v248, v47, v31 row_shl:1 row_mask:0xf bank_mask:0xf
	v_add_f32_e32 v79, 1.0, v79
	v_rcp_f32_e32 v91, v79
	v_fmac_f32_dpp v248, v85, v31 row_shr:15 row_mask:0xf bank_mask:0xf
	v_mov_b32_e32 v79, v248
	v_pk_mul_f32 v[74:75], v[74:75], v[78:79]
	v_pk_mul_f32 v[74:75], v[74:75], v[90:91]
	v_fmac_f32_dpp v249, v40, v64 row_shr:1 row_mask:0xf bank_mask:0xf
	v_fmac_f32_dpp v251, v48, v36 row_shr:1 row_mask:0xf bank_mask:0xf
	v_fma_f32 v183, v61, v41, v69
	v_fma_f32 v252, v29, v49, v45
	v_fmac_f32_dpp v249, v80, v64 row_shl:15 row_mask:0xf bank_mask:0xf
	v_fmac_f32_dpp v251, v76, v36 row_shl:15 row_mask:0xf bank_mask:0xf
	v_fmac_f32_dpp v183, v41, v65 row_shr:1 row_mask:0xf bank_mask:0xf
	v_fmac_f32_dpp v249, v40, v56 row_shl:1 row_mask:0xf bank_mask:0xf
	v_fmac_f32_dpp v251, v48, v32 row_shl:1 row_mask:0xf bank_mask:0xf
	v_fmac_f32_dpp v183, v81, v65 row_shl:15 row_mask:0xf bank_mask:0xf
	v_fmac_f32_dpp v249, v82, v56 row_shr:15 row_mask:0xf bank_mask:0xf
; #define PG8_GAS __attribute__((address_space(1)))
; __device__ __forceinline__ unsigned cvt_pk_bf16(float lo, float hi) { const f32x2c v = {lo, hi}; return __builtin_bit_cast(unsigned, __builtin_convertvector(v, bf16x2c)); }
; __device__ __forceinline__ float fma_s(float a, float b, float c) { float d; asm("v_fma_f32 %0, %1, %2, %3" : "=v"(d) : "v"(a), "v"(b), "v"(c)); return d; }
; #define PG8_ROR1(x) dpp_ror1(x)
; #define PG8_ROR15(x) dpp_ror15(x)
;     __device__ __forceinline__ void run(f32x4 (&acc)[2][2][4][2], const Unit& un, int wr, int wc, int fr, int fq, PG8_LAS unsigned char* xl) const {
;     ...
;                 for (int m = 0; m < 4; ++m) {
;                     float o[4];
; #pragma unroll
;                     for (int e = 0; e < 4; ++e) {
;                         const float g = acc[ai][0][m][n][e], v = acc[ai][1][m][n][e];
;                         const float gpe = m > 0 ? PG8_ROR1(acc[ai][0][m - 1][n][e]) : hpg[e], vpe = m > 0 ? PG8_ROR1(acc[ai][1][m - 1][n][e]) : hpv[e];
;                         const float gne = m < 3 ? PG8_ROR15(acc[ai][0][m + 1][n][e]) : hng[e], vne = m < 3 ? PG8_ROR15(acc[ai][1][m + 1][n][e]) : hnv[e];
;                         const float gpi = PG8_ROR1(g), vpi = PG8_ROR1(v), gni = PG8_ROR15(g), vni = PG8_ROR15(v);
;                         const float gp = e0 ? gpe : gpi, vp = e0 ? vpe : vpi, gn = e15 ? gne : gni, vn = e15 ? vne : vni;
;                         const float cg = fma_s(w2g[e], gn, fma_s(w1g[e], g, fma_s(w0g[e], gp, bg[e]))), cv = fma_s(w2v[e], vn, fma_s(w1v[e], v, fma_s(w0v[e], vp, bv[e])));
;                         o[e] = (cg * cv) * __builtin_amdgcn_rcpf(1.0f + __builtin_amdgcn_exp2f(cg * -1.4426950408889634f));
;                     }
;                     if (n == 0) { keep[m].x = cvt_pk_bf16(o[0], o[1]); keep[m].y = cvt_pk_bf16(o[2], o[3]); }
;                     else { u32x4 w; w.x = keep[m].x; w.y = keep[m].y; w.z = cvt_pk_bf16(o[0], o[1]); w.w = cvt_pk_bf16(o[2], o[3]);
;                         *(PG8_GAS u32x4*)(act + (size_t)(row0 + ai * HALF + m * 16) * dff + j - 4) = w; }
	v_mov_b32_e32 v76, v249
	v_mul_f32_e32 v78, 0xbfb8aa3b, v76
	v_exp_f32_e32 v90, v78
	v_fmac_f32_dpp v251, v8, v32 row_shr:15 row_mask:0xf bank_mask:0xf
	v_add_f32_e32 v79, 1.0, v90
	v_mov_b32_e32 v78, v251
	v_rcp_f32_e32 v80, v79
	v_fmac_f32_dpp v183, v41, v57 row_shl:1 row_mask:0xf bank_mask:0xf
	v_add_u32_e32 v92, 0x80, v172
	v_fmac_f32_dpp v252, v49, v37 row_shr:1 row_mask:0xf bank_mask:0xf
	v_fmac_f32_dpp v183, v83, v57 row_shr:15 row_mask:0xf bank_mask:0xf
	v_cvt_pk_bf16_f32 v90, v74, v75
	v_fmac_f32_dpp v252, v77, v37 row_shl:15 row_mask:0xf bank_mask:0xf
	v_mov_b32_e32 v77, v183
	v_mul_f32_e32 v79, 0xbfb8aa3b, v77
	v_exp_f32_e32 v79, v79
	v_fmac_f32_dpp v252, v49, v33 row_shl:1 row_mask:0xf bank_mask:0xf
	v_add_f32_e32 v79, 1.0, v79
	v_rcp_f32_e32 v81, v79
	v_fmac_f32_dpp v252, v9, v33 row_shr:15 row_mask:0xf bank_mask:0xf
	v_mov_b32_e32 v79, v252
	v_pk_mul_f32 v[76:77], v[76:77], v[78:79]
	v_pk_mul_f32 v[76:77], v[76:77], v[80:81]
	v_mov_b64_e32 v[74:75], s[24:25]
	v_cvt_pk_bf16_f32 v91, v76, v77
	v_mad_i64_i32 v[76:77], s[14:15], v92, s5, v[74:75]
	v_lshl_add_u64 v[76:77], v[76:77], 0, v[146:147]
	global_store_dwordx4 v[76:77], v[88:91], off
	v_fma_f32 v253, v26, v84, v42
	v_fma_f32 v181, v58, v86, v66
	v_fma_f32 v255, v59, v87, v67
	v_fmac_f32_dpp v253, v84, v34 row_shr:1 row_mask:0xf bank_mask:0xf
	v_fmac_f32_dpp v181, v86, v62 row_shr:1 row_mask:0xf bank_mask:0xf
	v_fmac_f32_dpp v255, v87, v63 row_shr:1 row_mask:0xf bank_mask:0xf
	v_fmac_f32_dpp v253, v46, v34 row_shl:15 row_mask:0xf bank_mask:0xf
	v_fmac_f32_dpp v181, v38, v62 row_shl:15 row_mask:0xf bank_mask:0xf
	v_fmac_f32_dpp v255, v39, v63 row_shl:15 row_mask:0xf bank_mask:0xf
	v_fmac_f32_dpp v253, v84, v30 row_shl:1 row_mask:0xf bank_mask:0xf
	v_fmac_f32_dpp v181, v86, v54 row_shl:1 row_mask:0xf bank_mask:0xf
	v_fmac_f32_dpp v255, v87, v55 row_shl:1 row_mask:0xf bank_mask:0xf
	v_fmac_f32_dpp v253, v14, v30 row_shr:15 row_mask:0xf bank_mask:0xf
	v_mov_b32_e32 v46, v253
	v_fmac_f32_dpp v181, v16, v54 row_shr:15 row_mask:0xf bank_mask:0xf
	v_mov_b32_e32 v38, v181
	v_mul_f32_e32 v76, 0xbfb8aa3b, v38
	v_fmac_f32_dpp v255, v17, v55 row_shr:15 row_mask:0xf bank_mask:0xf
	v_mov_b32_e32 v39, v255
	v_exp_f32_e32 v76, v76
	v_mul_f32_e32 v77, 0xbfb8aa3b, v39
	v_exp_f32_e32 v77, v77
	v_add_f32_e32 v76, 1.0, v76
	v_add_f32_e32 v77, 1.0, v77
	v_rcp_f32_e32 v76, v76
	v_rcp_f32_e32 v77, v77
	v_fma_f32 v179, v27, v85, v43
	v_fma_f32 v185, v60, v82, v68
	v_fma_f32 v250, v28, v8, v44
	v_fma_f32 v248, v28, v10, v44
	v_fma_f32 v249, v28, v20, v44
	v_fmac_f32_dpp v179, v85, v35 row_shr:1 row_mask:0xf bank_mask:0xf
	v_fmac_f32_dpp v185, v82, v64 row_shr:1 row_mask:0xf bank_mask:0xf
	v_fmac_f32_dpp v250, v8, v36 row_shr:1 row_mask:0xf bank_mask:0xf
	v_fmac_f32_dpp v179, v47, v35 row_shl:15 row_mask:0xf bank_mask:0xf
	v_fmac_f32_dpp v185, v40, v64 row_shl:15 row_mask:0xf bank_mask:0xf
	v_fmac_f32_dpp v250, v48, v36 row_shl:15 row_mask:0xf bank_mask:0xf
	v_fmac_f32_dpp v179, v85, v31 row_shl:1 row_mask:0xf bank_mask:0xf
	v_fmac_f32_dpp v185, v82, v56 row_shl:1 row_mask:0xf bank_mask:0xf
	v_fmac_f32_dpp v250, v8, v32 row_shl:1 row_mask:0xf bank_mask:0xf
	v_fmac_f32_dpp v179, v15, v31 row_shr:15 row_mask:0xf bank_mask:0xf
	v_mov_b32_e32 v47, v179
	v_pk_mul_f32 v[38:39], v[38:39], v[46:47]
	v_pk_mul_f32 v[38:39], v[38:39], v[76:77]
	v_fmac_f32_dpp v185, v12, v56 row_shr:15 row_mask:0xf bank_mask:0xf
	v_mov_b32_e32 v40, v185
	v_mul_f32_e32 v47, 0xbfb8aa3b, v40
	v_exp_f32_e32 v47, v47
	v_fmac_f32_dpp v250, v10, v32 row_shr:15 row_mask:0xf bank_mask:0xf
	v_add_f32_e32 v46, 1.0, v47
	v_fma_f32 v251, v61, v83, v69
	v_rcp_f32_e32 v46, v46
	v_fma_f32 v183, v29, v9, v45
	v_fma_f32 v252, v29, v11, v45
	v_fma_f32 v253, v29, v21, v45
	v_fmac_f32_dpp v251, v83, v65 row_shr:1 row_mask:0xf bank_mask:0xf
	v_fmac_f32_dpp v183, v9, v37 row_shr:1 row_mask:0xf bank_mask:0xf
	v_fma_f32 v181, v58, v16, v66
	v_fmac_f32_dpp v251, v41, v65 row_shl:15 row_mask:0xf bank_mask:0xf
	v_fmac_f32_dpp v183, v49, v37 row_shl:15 row_mask:0xf bank_mask:0xf
	v_fmac_f32_dpp v181, v16, v62 row_shr:1 row_mask:0xf bank_mask:0xf
	v_fmac_f32_dpp v251, v83, v57 row_shl:1 row_mask:0xf bank_mask:0xf
	v_fmac_f32_dpp v183, v9, v33 row_shl:1 row_mask:0xf bank_mask:0xf
	v_fmac_f32_dpp v181, v86, v62 row_shl:15 row_mask:0xf bank_mask:0xf
	v_fmac_f32_dpp v251, v13, v57 row_shr:15 row_mask:0xf bank_mask:0xf
	v_mov_b32_e32 v41, v251
	v_fmac_f32_dpp v183, v11, v33 row_shr:15 row_mask:0xf bank_mask:0xf
	v_fmac_f32_dpp v181, v16, v54 row_shl:1 row_mask:0xf bank_mask:0xf
	v_fma_f32 v255, v26, v14, v42
	v_fmac_f32_dpp v248, v10, v36 row_shr:1 row_mask:0xf bank_mask:0xf
	v_fmac_f32_dpp v181, v22, v54 row_shr:15 row_mask:0xf bank_mask:0xf
	v_fmac_f32_dpp v255, v14, v34 row_shr:1 row_mask:0xf bank_mask:0xf
	v_fmac_f32_dpp v248, v8, v36 row_shl:15 row_mask:0xf bank_mask:0xf
	v_mov_b32_e32 v8, v250
	v_fmac_f32_dpp v255, v84, v34 row_shl:15 row_mask:0xf bank_mask:0xf
	v_fma_f32 v179, v59, v17, v67
	v_fmac_f32_dpp v248, v10, v32 row_shl:1 row_mask:0xf bank_mask:0xf
	v_fmac_f32_dpp v255, v14, v30 row_shl:1 row_mask:0xf bank_mask:0xf
	v_fmac_f32_dpp v179, v17, v63 row_shr:1 row_mask:0xf bank_mask:0xf
	v_fmac_f32_dpp v248, v20, v32 row_shr:15 row_mask:0xf bank_mask:0xf
	v_fmac_f32_dpp v255, v18, v30 row_shr:15 row_mask:0xf bank_mask:0xf
	v_fmac_f32_dpp v179, v87, v63 row_shl:15 row_mask:0xf bank_mask:0xf
	v_fmac_f32_dpp v252, v11, v37 row_shr:1 row_mask:0xf bank_mask:0xf
	v_fmac_f32_dpp v249, v20, v36 row_shr:1 row_mask:0xf bank_mask:0xf
	v_fmac_f32_dpp v179, v17, v55 row_shl:1 row_mask:0xf bank_mask:0xf
	v_fmac_f32_dpp v252, v9, v37 row_shl:15 row_mask:0xf bank_mask:0xf
; #define PG8_GAS __attribute__((address_space(1)))
; #define PG8_ROR1(x) dpp_ror1(x)
; #define PG8_ROR15(x) dpp_ror15(x)
;     __device__ __forceinline__ void run(f32x4 (&acc)[2][2][4][2], const Unit& un, int wr, int wc, int fr, int fq, PG8_LAS unsigned char* xl) const {
;     ...
;                 for (int m = 0; m < 4; ++m) {
;                     float o[4];
; #pragma unroll
;                     for (int e = 0; e < 4; ++e) {
;                         const float g = acc[ai][0][m][n][e], v = acc[ai][1][m][n][e];
;                         const float gpe = m > 0 ? PG8_ROR1(acc[ai][0][m - 1][n][e]) : hpg[e], vpe = m > 0 ? PG8_ROR1(acc[ai][1][m - 1][n][e]) : hpv[e];
;                         const float gne = m < 3 ? PG8_ROR15(acc[ai][0][m + 1][n][e]) : hng[e], vne = m < 3 ? PG8_ROR15(acc[ai][1][m + 1][n][e]) : hnv[e];
;                         const float gpi = PG8_ROR1(g), vpi = PG8_ROR1(v), gni = PG8_ROR15(g), vni = PG8_ROR15(v);
;                         const float gp = e0 ? gpe : gpi, vp = e0 ? vpe : vpi, gn = e15 ? gne : gni, vn = e15 ? vne : vni;
;                         const float cg = fma_s(w2g[e], gn, fma_s(w1g[e], g, fma_s(w0g[e], gp, bg[e]))), cv = fma_s(w2v[e], vn, fma_s(w1v[e], v, fma_s(w0v[e], vp, bv[e])));
;                         o[e] = (cg * cv) * __builtin_amdgcn_rcpf(1.0f + __builtin_amdgcn_exp2f(cg * -1.4426950408889634f));
;                     }
;                     if (n == 0) { keep[m].x = cvt_pk_bf16(o[0], o[1]); keep[m].y = cvt_pk_bf16(o[2], o[3]); }
;                     else { u32x4 w; w.x = keep[m].x; w.y = keep[m].y; w.z = cvt_pk_bf16(o[0], o[1]); w.w = cvt_pk_bf16(o[2], o[3]);
;                         *(PG8_GAS u32x4*)(act + (size_t)(row0 + ai * HALF + m * 16) * dff + j - 4) = w; }
; template <class Epi, class Sched, bool ALIGN_EPI = false, bool SP2 = false, bool F8 = false>
; __device__ __forceinline__ void gemm_phase(PG8_LAS unsigned char* lds, const Gemm g, const Sched& S, const Epi& E) {
;     ...
;         if (!has_next) break;
; #pragma unroll
;         for (int a = 0; a < 2; ++a)
; #pragma unroll
;             for (int b = 0; b < 2; ++b)
; #pragma unroll
;                 for (int m = 0; m < 4; ++m)
; #pragma unroll
;                     for (int n = 0; n < 2; ++n) acc[a][b][m][n] = (f32x4){0.f, 0.f, 0.f, 0.f};
;         cur = nxt; cA = nA; cB = nB; ++ui;
;         if constexpr (ALIGN_EPI) { if (wr == 1) PG8_BAR; }
;     }
	v_mov_b32_e32 v9, v183
	v_pk_mul_f32 v[8:9], v[40:41], v[8:9]
	v_fmac_f32_dpp v179, v23, v55 row_shr:15 row_mask:0xf bank_mask:0xf
	v_fma_f32 v185, v27, v15, v43
	v_fmac_f32_dpp v252, v11, v33 row_shl:1 row_mask:0xf bank_mask:0xf
	v_fmac_f32_dpp v249, v10, v36 row_shl:15 row_mask:0xf bank_mask:0xf
	v_fmac_f32_dpp v185, v15, v35 row_shr:1 row_mask:0xf bank_mask:0xf
	v_mov_b32_e32 v10, v248
	v_fma_f32 v251, v60, v12, v68
	v_fmac_f32_dpp v185, v85, v35 row_shl:15 row_mask:0xf bank_mask:0xf
	v_fmac_f32_dpp v252, v21, v33 row_shr:15 row_mask:0xf bank_mask:0xf
	v_fmac_f32_dpp v251, v12, v64 row_shr:1 row_mask:0xf bank_mask:0xf
	v_fmac_f32_dpp v185, v15, v31 row_shl:1 row_mask:0xf bank_mask:0xf
	v_fmac_f32_dpp v249, v20, v32 row_shl:1 row_mask:0xf bank_mask:0xf
	v_fmac_f32_dpp v251, v82, v64 row_shl:15 row_mask:0xf bank_mask:0xf
	v_fmac_f32_dpp v185, v19, v31 row_shr:15 row_mask:0xf bank_mask:0xf
	v_fmac_f32_dpp v249, v52, v32 row_shr:15 row_mask:0xf bank_mask:0xf
	v_fmac_f32_dpp v251, v12, v56 row_shl:1 row_mask:0xf bank_mask:0xf
	v_fmac_f32_dpp v253, v21, v37 row_shr:1 row_mask:0xf bank_mask:0xf
	v_fma_f32 v250, v61, v13, v69
	v_fmac_f32_dpp v251, v24, v56 row_shr:15 row_mask:0xf bank_mask:0xf
	v_fmac_f32_dpp v253, v11, v37 row_shl:15 row_mask:0xf bank_mask:0xf
	v_fmac_f32_dpp v250, v13, v65 row_shr:1 row_mask:0xf bank_mask:0xf
	v_mov_b32_e32 v11, v252
	v_fmac_f32_dpp v253, v21, v33 row_shl:1 row_mask:0xf bank_mask:0xf
	v_fmac_f32_dpp v250, v83, v65 row_shl:15 row_mask:0xf bank_mask:0xf
	v_mul_f32_e32 v83, 0xbfb8aa3b, v41
	v_exp_f32_e32 v83, v83
	v_fmac_f32_dpp v250, v13, v57 row_shl:1 row_mask:0xf bank_mask:0xf
	v_add_f32_e32 v47, 1.0, v83
	v_rcp_f32_e32 v47, v47
	v_fmac_f32_dpp v250, v25, v57 row_shr:15 row_mask:0xf bank_mask:0xf
	v_pk_mul_f32 v[40:41], v[8:9], v[46:47]
	v_cvt_pk_bf16_f32 v8, v38, v39
	v_add_u32_e32 v38, 0x90, v172
	v_mad_i64_i32 v[38:39], s[14:15], v38, s5, v[74:75]
	v_cvt_pk_bf16_f32 v9, v40, v41
	v_lshl_add_u64 v[38:39], v[38:39], 0, v[146:147]
	global_store_dwordx4 v[38:39], v[6:9], off
	v_fmac_f32_dpp v253, v53, v33 row_shr:15 row_mask:0xf bank_mask:0xf
	v_fma_f32 v183, v58, v22, v66
	v_mov_b32_e32 v6, v181
	v_mul_f32_e32 v8, 0xbfb8aa3b, v6
	v_mov_b32_e32 v9, v185
	v_fmac_f32_dpp v183, v22, v62 row_shr:1 row_mask:0xf bank_mask:0xf
	v_fma_f32 v248, v26, v18, v42
	v_fma_f32 v252, v59, v23, v67
	v_fmac_f32_dpp v183, v16, v62 row_shl:15 row_mask:0xf bank_mask:0xf
	v_exp_f32_e32 v16, v8
	v_mov_b32_e32 v8, v255
	v_add_f32_e32 v7, 1.0, v16
	v_rcp_f32_e32 v16, v7
	v_mov_b32_e32 v7, v179
	v_fmac_f32_dpp v183, v22, v54 row_shl:1 row_mask:0xf bank_mask:0xf
	v_fmac_f32_dpp v248, v18, v34 row_shr:1 row_mask:0xf bank_mask:0xf
	v_fmac_f32_dpp v252, v23, v63 row_shr:1 row_mask:0xf bank_mask:0xf
	v_fmac_f32_dpp v183, v70, v54 row_shr:15 row_mask:0xf bank_mask:0xf
	v_fmac_f32_dpp v248, v14, v34 row_shl:15 row_mask:0xf bank_mask:0xf
	v_fmac_f32_dpp v252, v17, v63 row_shl:15 row_mask:0xf bank_mask:0xf
	v_mul_f32_e32 v17, 0xbfb8aa3b, v7
	v_exp_f32_e32 v17, v17
	v_pk_mul_f32 v[6:7], v[6:7], v[8:9]
	v_add_f32_e32 v17, 1.0, v17
	v_rcp_f32_e32 v17, v17
	v_mov_b32_e32 v8, v251
	v_pk_mul_f32 v[6:7], v[6:7], v[16:17]
	v_cvt_pk_bf16_f32 v6, v6, v7
	v_fmac_f32_dpp v248, v18, v30 row_shl:1 row_mask:0xf bank_mask:0xf
	v_fmac_f32_dpp v252, v23, v55 row_shl:1 row_mask:0xf bank_mask:0xf
	v_fma_f32 v181, v27, v19, v43
	v_fmac_f32_dpp v248, v50, v30 row_shr:15 row_mask:0xf bank_mask:0xf
	v_fmac_f32_dpp v252, v71, v55 row_shr:15 row_mask:0xf bank_mask:0xf
	v_fmac_f32_dpp v181, v19, v35 row_shr:1 row_mask:0xf bank_mask:0xf
	v_fma_f32 v185, v60, v24, v68
	v_fma_f32 v255, v61, v25, v69
	v_fmac_f32_dpp v181, v15, v35 row_shl:15 row_mask:0xf bank_mask:0xf
	v_fmac_f32_dpp v185, v24, v64 row_shr:1 row_mask:0xf bank_mask:0xf
	v_fmac_f32_dpp v255, v25, v65 row_shr:1 row_mask:0xf bank_mask:0xf
	v_fmac_f32_dpp v181, v19, v31 row_shl:1 row_mask:0xf bank_mask:0xf
	v_fmac_f32_dpp v185, v12, v64 row_shl:15 row_mask:0xf bank_mask:0xf
	v_mul_f32_e32 v12, 0xbfb8aa3b, v8
	v_exp_f32_e32 v12, v12
	v_fmac_f32_dpp v181, v51, v31 row_shr:15 row_mask:0xf bank_mask:0xf
	v_add_f32_e32 v9, 1.0, v12
	v_rcp_f32_e32 v12, v9
	v_mov_b32_e32 v9, v250
	v_fmac_f32_dpp v185, v24, v56 row_shl:1 row_mask:0xf bank_mask:0xf
	v_fmac_f32_dpp v255, v13, v65 row_shl:15 row_mask:0xf bank_mask:0xf
	v_mul_f32_e32 v13, 0xbfb8aa3b, v9
	v_exp_f32_e32 v13, v13
	v_pk_mul_f32 v[8:9], v[8:9], v[10:11]
	v_add_f32_e32 v13, 1.0, v13
	v_rcp_f32_e32 v13, v13
	v_fmac_f32_dpp v185, v72, v56 row_shr:15 row_mask:0xf bank_mask:0xf
	v_pk_mul_f32 v[8:9], v[8:9], v[12:13]
	v_cvt_pk_bf16_f32 v7, v8, v9
	v_add_u32_e32 v8, 0xa0, v172
	v_mad_i64_i32 v[8:9], s[14:15], v8, s5, v[74:75]
	v_lshl_add_u64 v[8:9], v[8:9], 0, v[146:147]
	global_store_dwordx4 v[8:9], v[4:7], off
	v_fmac_f32_dpp v255, v25, v57 row_shl:1 row_mask:0xf bank_mask:0xf
	s_nop 0
	v_mov_b32_e32 v4, v183
	v_mul_f32_e32 v6, 0xbfb8aa3b, v4
	v_exp_f32_e32 v8, v6
	v_mov_b32_e32 v6, v248
	v_add_f32_e32 v5, 1.0, v8
	v_rcp_f32_e32 v8, v5
	v_mov_b32_e32 v5, v252
	v_mul_f32_e32 v9, 0xbfb8aa3b, v5
	v_exp_f32_e32 v9, v9
	v_mov_b32_e32 v7, v181
	v_add_f32_e32 v9, 1.0, v9
	v_rcp_f32_e32 v9, v9
	v_pk_mul_f32 v[4:5], v[4:5], v[6:7]
	v_pk_mul_f32 v[4:5], v[4:5], v[8:9]
	v_mov_b32_e32 v6, v185
	v_mul_f32_e32 v8, 0xbfb8aa3b, v6
	v_exp_f32_e32 v10, v8
	v_mov_b32_e32 v8, v249
	v_add_f32_e32 v7, 1.0, v10
	v_rcp_f32_e32 v10, v7
	v_cvt_pk_bf16_f32 v4, v4, v5
	v_fmac_f32_dpp v255, v73, v57 row_shr:15 row_mask:0xf bank_mask:0xf
	v_mov_b32_e32 v7, v255
	v_mul_f32_e32 v11, 0xbfb8aa3b, v7
	v_exp_f32_e32 v11, v11
	v_mov_b32_e32 v9, v253
	v_pk_mul_f32 v[6:7], v[6:7], v[8:9]
	v_add_f32_e32 v11, 1.0, v11
	v_rcp_f32_e32 v11, v11
	s_nop 0
	v_pk_mul_f32 v[6:7], v[6:7], v[10:11]
	v_cvt_pk_bf16_f32 v5, v6, v7
	v_add_u32_e32 v6, 0xb0, v172
	v_mad_i64_i32 v[6:7], s[10:11], v6, s5, v[74:75]
	v_lshl_add_u64 v[6:7], v[6:7], 0, v[146:147]
	global_store_dwordx4 v[6:7], v[2:5], off
	v_mov_b32_e32 v179, 0
	v_mov_b32_e32 v181, 0
	v_mov_b32_e32 v183, 0
	v_mov_b32_e32 v185, 0
	s_andn2_b64 vcc, exec, s[8:9]
	s_mov_b64 s[8:9], -1
	s_cbranch_vccnz .LBB0_766
	s_andn2_b64 vcc, exec, s[30:31]
	s_cbranch_vccnz .LBB0_765
	s_barrier
	s_branch .LBB0_765

; __global__ void __launch_bounds__(NWAVES * 64, 2) fwd_kernel(Args args) {
	.amdhsa_kernel _Z10fwd_kernel4Args
		.amdhsa_group_segment_fixed_size 0
		.amdhsa_private_segment_fixed_size 0
		.amdhsa_kernarg_size 400
		.amdhsa_user_sgpr_count 2
		.amdhsa_user_sgpr_dispatch_ptr 0
		.amdhsa_user_sgpr_queue_ptr 0
		.amdhsa_user_sgpr_kernarg_segment_ptr 1
		.amdhsa_user_sgpr_dispatch_id 0
		.amdhsa_user_sgpr_kernarg_preload_length 0
		.amdhsa_user_sgpr_kernarg_preload_offset 0
		.amdhsa_user_sgpr_private_segment_size 0
		.amdhsa_uses_dynamic_stack 0
		.amdhsa_enable_private_segment 0
		.amdhsa_system_sgpr_workgroup_id_x 1
		.amdhsa_system_sgpr_workgroup_id_y 0
		.amdhsa_system_sgpr_workgroup_id_z 0
		.amdhsa_system_sgpr_workgroup_info 0
		.amdhsa_system_vgpr_workitem_id 0
		.amdhsa_next_free_vgpr 256
		.amdhsa_next_free_sgpr 102
		.amdhsa_accum_offset 256
		.amdhsa_reserve_vcc 1
		.amdhsa_float_round_mode_32 0
		.amdhsa_float_round_mode_16_64 0
		.amdhsa_float_denorm_mode_32 3
		.amdhsa_float_denorm_mode_16_64 3
		.amdhsa_dx10_clamp 1
		.amdhsa_ieee_mode 1
		.amdhsa_fp16_overflow 0
		.amdhsa_tg_split 0
		.amdhsa_exception_fp_ieee_invalid_op 0
		.amdhsa_exception_fp_denorm_src 0
		.amdhsa_exception_fp_ieee_div_zero 0
		.amdhsa_exception_fp_ieee_overflow 0
		.amdhsa_exception_fp_ieee_underflow 0
		.amdhsa_exception_fp_ieee_inexact 0
		.amdhsa_exception_int_div_zero 0
	.end_amdhsa_kernel

; template <int OFF> __device__ __forceinline__ unsigned long long karg_u64() {
;     auto kp = __builtin_amdgcn_kernarg_segment_ptr(); unsigned long long v;
;     asm volatile("s_load_dwordx2 %0, %1, %2\n\ts_waitcnt lgkmcnt(0)" : "=s"(v) : "s"(kp), "i"(OFF) : "memory"); return v;
; }
; __global__ void __launch_bounds__(NWAVES * 64, 2) fwd_kernel(Args args) {
amdhsa.kernels:
  - .agpr_count:     0
    .args:
      - .offset:         0
        .size:           144
        .value_kind:     by_value
      - .offset:         144
        .size:           4
        .value_kind:     hidden_block_count_x
      - .offset:         148
        .size:           4
        .value_kind:     hidden_block_count_y
      - .offset:         152
        .size:           4
        .value_kind:     hidden_block_count_z
      - .offset:         156
        .size:           2
        .value_kind:     hidden_group_size_x
      - .offset:         158
        .size:           2
        .value_kind:     hidden_group_size_y
      - .offset:         160
        .size:           2
        .value_kind:     hidden_group_size_z
      - .offset:         162
        .size:           2
        .value_kind:     hidden_remainder_x
      - .offset:         164
        .size:           2
        .value_kind:     hidden_remainder_y
      - .offset:         166
        .size:           2
        .value_kind:     hidden_remainder_z
      - .offset:         184
        .size:           8
        .value_kind:     hidden_global_offset_x
      - .offset:         192
        .size:           8
        .value_kind:     hidden_global_offset_y
      - .offset:         200
        .size:           8
        .value_kind:     hidden_global_offset_z
      - .offset:         208
        .size:           2
        .value_kind:     hidden_grid_dims
      - .offset:         264
        .size:           4
        .value_kind:     hidden_dynamic_lds_size
    .group_segment_fixed_size: 0
    .kernarg_segment_align: 8
    .kernarg_segment_size: 400
    .language:       OpenCL C
    .language_version:
      - 2
      - 0
    .max_flat_workgroup_size: 512
    .name:           _Z10fwd_kernel4Args
    .private_segment_fixed_size: 0
    .sgpr_count:     108
    .sgpr_spill_count: 53
    .symbol:         _Z10fwd_kernel4Args.kd
    .uniform_work_group_size: 1
    .uses_dynamic_stack: false
    .vgpr_count:     256
    .vgpr_spill_count: 0
    .wavefront_size: 64
